# diff attn: pipelined masked+unmasked tile bodies, pipelined partial-sum loads; swiglu epilogue ssq loads hoisted; grid barrier acquire invalidate issued before the spin (8 of 10 barriers)
# speedup vs baseline: 1.0655x; 1.0156x over previous
.LBB0_344:
	s_or_b64 exec, exec, s[8:9]
	v_cvt_f32_u32_e32 v4, v2
	s_waitcnt vmcnt(0)
	v_readfirstlane_b32 s2, v3
	v_sub_u32_e32 v3, 0, v2
	v_rcp_iflag_f32_e32 v4, v4
	v_add_u32_e32 v5, s2, v1
	v_mul_f32_e32 v4, 0x4f7ffffe, v4
	v_cvt_u32_f32_e32 v4, v4
	v_mul_lo_u32 v1, v3, v4
	v_mul_hi_u32 v1, v4, v1
	v_add_u32_e32 v1, v4, v1
	v_mul_hi_u32 v1, v5, v1
	v_mul_lo_u32 v3, v1, v2
	v_sub_u32_e32 v3, v5, v3
	v_add_u32_e32 v4, 1, v1
	v_cmp_ge_u32_e32 vcc, v3, v2
	s_nop 1
	v_cndmask_b32_e32 v1, v1, v4, vcc
	v_sub_u32_e32 v4, v3, v2
	v_cndmask_b32_e32 v3, v3, v4, vcc
	v_add_u32_e32 v4, 1, v1
	v_cmp_ge_u32_e32 vcc, v3, v2
	v_add_u32_e32 v3, 1, v5
	s_nop 0
	v_cndmask_b32_e32 v1, v1, v4, vcc
	v_mul_lo_u32 v4, v2, v1
	v_add_u32_e32 v2, v4, v2
	v_cmp_ne_u32_e32 vcc, v3, v2
	s_and_saveexec_b64 s[2:3], vcc
	s_xor_b64 s[6:7], exec, s[2:3]
	s_cbranch_execz .LBB0_358
	s_waitcnt lgkmcnt(0)
	v_mov_b32_e32 v0, 0x2000
	buffer_inv sc1
	global_load_dword v0, v0, s[4:5] offset:1024 sc1
	s_add_u32 s12, s4, 0x2400
	s_addc_u32 s13, s5, 0
	s_waitcnt vmcnt(0)
	v_cmp_eq_u32_e32 vcc, v0, v1
	s_and_saveexec_b64 s[8:9], vcc
	s_cbranch_execz .LBB0_357
	s_add_u32 s10, s74, 0xfa00200
	s_addc_u32 s11, s75, 0
	s_mov_b32 s2, 1
	s_mov_b64 s[14:15], 0
	v_mov_b32_e32 v0, 0
	s_branch .LBB0_348

.LBB0_357:
	s_or_b64 exec, exec, s[8:9]
	s_waitcnt vmcnt(0)
	s_waitcnt vmcnt(0)

.LBB0_361:
	s_or_b64 exec, exec, s[8:9]
	v_cvt_f32_u32_e32 v3, v0
	s_waitcnt vmcnt(0)
	buffer_inv sc1
	v_readfirstlane_b32 s2, v2
	s_add_u32 s8, s74, 0xfa03500
	s_addc_u32 s9, s75, 0
	v_rcp_iflag_f32_e32 v3, v3
	v_add_u32_e32 v1, s2, v1
	v_add_u32_e32 v4, 1, v1
	s_mov_b64 s[10:11], -1
	v_mul_f32_e32 v2, 0x4f7ffffe, v3
	v_cvt_u32_f32_e32 v2, v2
	v_sub_u32_e32 v3, 0, v0
	v_mul_lo_u32 v3, v3, v2
	v_mul_hi_u32 v3, v2, v3
	v_add_u32_e32 v2, v2, v3
	v_mul_hi_u32 v2, v1, v2
	v_mul_lo_u32 v3, v2, v0
	v_sub_u32_e32 v1, v1, v3
	v_add_u32_e32 v5, 1, v2
	v_cmp_ge_u32_e32 vcc, v1, v0
	v_sub_u32_e32 v3, v1, v0
	s_nop 0
	v_cndmask_b32_e32 v2, v2, v5, vcc
	v_cndmask_b32_e32 v1, v1, v3, vcc
	v_add_u32_e32 v3, 1, v2
	v_cmp_ge_u32_e32 vcc, v1, v0
	s_nop 1
	v_cndmask_b32_e32 v2, v2, v3, vcc
	v_mul_lo_u32 v1, v0, v2
	v_add_u32_e32 v0, v1, v0
	v_cmp_ne_u32_e32 vcc, v4, v0
	v_mov_b64_e32 v[0:1], s[8:9]
	s_and_saveexec_b64 s[6:7], vcc
	s_cbranch_execz .LBB0_373
	v_mov_b32_e32 v0, 0
	global_load_dword v1, v0, s[8:9] sc1
	s_mov_b64 s[14:15], 0
	s_waitcnt vmcnt(0)
	v_cmp_eq_u32_e32 vcc, v1, v2
	s_and_saveexec_b64 s[12:13], vcc
	s_cbranch_execz .LBB0_372
	s_add_u32 s10, s74, 0xfa00200
	s_addc_u32 s11, s75, 0
	s_mov_b32 s2, 1
	s_branch .LBB0_365

.LBB0_375:
	s_or_b64 exec, exec, s[6:7]
	s_mov_b64 s[6:7], exec
	v_mbcnt_lo_u32_b32 v0, s6, 0
	v_mbcnt_hi_u32_b32 v0, s7, v0
	v_cmp_eq_u32_e32 vcc, 0, v0
	s_waitcnt vmcnt(0)
	s_and_saveexec_b64 s[8:9], vcc
	s_cbranch_execz .LBB0_377
	s_bcnt1_i32_b64 s2, s[6:7]
	v_mov_b32_e32 v0, 0x2000
	v_mov_b32_e32 v1, s2
	global_atomic_add v0, v1, s[4:5] offset:1024

.Ldiff_mask0:
	s_lshl_b32 s1, s0, 16
	v_add3_u32 v14, s1, v215, v216
	v_add3_u32 v15, s1, v195, v224
	s_sub_i32 s0, s35, 0x7f
	v_sub_u32_e32 v218, v193, v194
	v_subrev_u32_e32 v218, s0, v218
	ds_read_b128 v[2:5], v14
	v_xor_b32_e32 v217, 32, v14
	ds_read_b128 v[6:9], v217
	s_waitcnt lgkmcnt(1)
	v_mfma_f32_32x32x16_bf16 v[144:159], v[2:5], v[160:163], 0
	v_xor_b32_e32 v222, 64, v14
	ds_read_b128 v[10:13], v222
	s_waitcnt lgkmcnt(1)
	v_mfma_f32_32x32x16_bf16 v[144:159], v[6:9], v[164:167], v[144:159]
	v_xor_b32_e32 v223, 0x60, v14
	ds_read_b128 v[2:5], v223
	s_waitcnt lgkmcnt(1)
	v_mfma_f32_32x32x16_bf16 v[144:159], v[10:13], v[168:171], v[144:159]
	v_xor_b32_e32 v225, 0x80, v14
	ds_read_b128 v[6:9], v225
	s_waitcnt lgkmcnt(1)
	v_mfma_f32_32x32x16_bf16 v[144:159], v[2:5], v[172:175], v[144:159]
	v_xor_b32_e32 v230, 0xa0, v14
	ds_read_b128 v[10:13], v230
	s_waitcnt lgkmcnt(1)
	v_mfma_f32_32x32x16_bf16 v[236:251], v[6:9], v[176:179], 0
	v_xor_b32_e32 v231, 0xc0, v14
	ds_read_b128 v[2:5], v231
	s_waitcnt lgkmcnt(1)
	v_mfma_f32_32x32x16_bf16 v[236:251], v[10:13], v[180:183], v[236:251]
	v_xor_b32_e32 v235, 0xe0, v14
	ds_read_b128 v[6:9], v235
	v_cmp_ge_i32_e64 s[4:5], v218, 0
	v_cmp_ge_i32_e64 s[6:7], v218, 1
	v_cmp_ge_i32_e64 s[10:11], v218, 2
	v_cmp_ge_i32_e64 s[20:21], v218, 3
	v_cmp_ge_i32_e64 s[46:47], v218, 4
	v_cmp_ge_i32_e64 s[48:49], v218, 5
	v_cmp_ge_i32_e64 s[50:51], v218, 6
	v_cmp_ge_i32_e64 s[76:77], v218, 7
	s_waitcnt lgkmcnt(1)
	v_mfma_f32_32x32x16_bf16 v[236:251], v[2:5], v[184:187], v[236:251]
	ds_read_b128 v[10:13], v15 offset:32768
	v_cmp_ge_i32_e64 s[84:85], v218, 16
	v_cmp_ge_i32_e64 s[86:87], v218, 17
	v_cmp_ge_i32_e64 s[88:89], v218, 18
	v_cmp_ge_i32_e64 s[90:91], v218, 19
	s_waitcnt lgkmcnt(1)
	v_mfma_f32_32x32x16_bf16 v[236:251], v[6:9], v[188:191], v[236:251]
	ds_read_b128 v[2:5], v15 offset:40960
	v_cmp_ge_i32_e64 s[92:93], v218, 20
	v_cmp_ge_i32_e64 s[94:95], v218, 21
	v_cmp_ge_i32_e64 s[96:97], v218, 22
	v_cmp_ge_i32_e64 vcc, v218, 23
	v_exp_f32_e32 v144, v144
	v_exp_f32_e32 v145, v145
	v_cndmask_b32_e64 v144, 0, v144, s[4:5]
	v_exp_f32_e32 v146, v146
	v_cndmask_b32_e64 v145, 0, v145, s[6:7]
	v_exp_f32_e32 v147, v147
	v_cndmask_b32_e64 v146, 0, v146, s[10:11]
	v_add_f32_e32 v0, v144, v145
	v_cvt_pk_bf16_f32 v144, v144, v145
	v_exp_f32_e32 v148, v148
	v_cndmask_b32_e64 v147, 0, v147, s[20:21]
	v_add_f32_e32 v0, v146, v0
	v_exp_f32_e32 v149, v149
	v_cndmask_b32_e64 v148, 0, v148, s[46:47]
	v_add_f32_e32 v0, v147, v0
	v_cvt_pk_bf16_f32 v145, v146, v147
	v_exp_f32_e32 v150, v150
	v_cndmask_b32_e64 v149, 0, v149, s[48:49]
	v_add_f32_e32 v0, v148, v0
	v_exp_f32_e32 v151, v151
	v_cndmask_b32_e64 v150, 0, v150, s[50:51]
	v_add_f32_e32 v0, v149, v0
	v_cvt_pk_bf16_f32 v146, v148, v149
	v_exp_f32_e32 v152, v152
	v_cndmask_b32_e64 v151, 0, v151, s[76:77]
	v_add_f32_e32 v0, v150, v0
	v_exp_f32_e32 v153, v153
	v_cndmask_b32_e64 v152, 0, v152, s[84:85]
	v_add_f32_e32 v0, v151, v0
	v_cvt_pk_bf16_f32 v147, v150, v151
	s_waitcnt lgkmcnt(1)
	s_nop 0
	v_mfma_f32_32x32x16_bf16 v[128:143], v[10:13], v[144:147], v[128:143]
	ds_read_b128 v[6:9], v15 offset:49152
	v_exp_f32_e32 v154, v154
	v_cndmask_b32_e64 v153, 0, v153, s[86:87]
	v_add_f32_e32 v0, v152, v0
	v_exp_f32_e32 v155, v155
	s_waitcnt lgkmcnt(1)
	v_mfma_f32_32x32x16_bf16 v[112:127], v[2:5], v[144:147], v[112:127]
	ds_read_b128 v[10:13], v15 offset:57344
	v_cndmask_b32_e64 v154, 0, v154, s[88:89]
	v_add_f32_e32 v0, v153, v0
	v_cvt_pk_bf16_f32 v148, v152, v153
	v_exp_f32_e32 v156, v156
	s_waitcnt lgkmcnt(1)
	v_mfma_f32_32x32x16_bf16 v[96:111], v[6:9], v[144:147], v[96:111]
	v_xor_b32_e32 v252, 32, v15
	ds_read_b128 v[2:5], v252 offset:32768
	v_cndmask_b32_e64 v155, 0, v155, s[90:91]
	v_add_f32_e32 v0, v154, v0
	v_exp_f32_e32 v157, v157
	v_cndmask_b32_e64 v156, 0, v156, s[92:93]
	s_waitcnt lgkmcnt(1)
	v_mfma_f32_32x32x16_bf16 v[80:95], v[10:13], v[144:147], v[80:95]
	ds_read_b128 v[6:9], v252 offset:40960
	v_add_f32_e32 v0, v155, v0
	v_cvt_pk_bf16_f32 v149, v154, v155
	v_exp_f32_e32 v158, v158
	v_cndmask_b32_e64 v157, 0, v157, s[94:95]
	v_add_f32_e32 v0, v156, v0
	v_exp_f32_e32 v159, v159
	v_cndmask_b32_e64 v158, 0, v158, s[96:97]
	v_add_f32_e32 v0, v157, v0
	v_cvt_pk_bf16_f32 v150, v156, v157
	v_cndmask_b32_e64 v159, 0, v159, vcc
	v_add_f32_e32 v0, v158, v0
	v_add_f32_e32 v0, v159, v0
	v_cvt_pk_bf16_f32 v151, v158, v159
	s_waitcnt lgkmcnt(1)
	s_nop 0
	v_mfma_f32_32x32x16_bf16 v[128:143], v[2:5], v[148:151], v[128:143]
	ds_read_b128 v[10:13], v252 offset:49152
	v_add_f32_e32 v197, v197, v0
	v_exp_f32_e32 v236, v236
	v_exp_f32_e32 v237, v237
	v_cndmask_b32_e64 v236, 0, v236, s[4:5]
	s_waitcnt lgkmcnt(1)
	v_mfma_f32_32x32x16_bf16 v[112:127], v[6:9], v[148:151], v[112:127]
	ds_read_b128 v[2:5], v252 offset:57344
	v_exp_f32_e32 v238, v238
	v_cndmask_b32_e64 v237, 0, v237, s[6:7]
	v_exp_f32_e32 v239, v239
	v_cndmask_b32_e64 v238, 0, v238, s[10:11]
	s_waitcnt lgkmcnt(1)
	v_mfma_f32_32x32x16_bf16 v[96:111], v[10:13], v[148:151], v[96:111]
	ds_read_b128 v[6:9], v14 offset:8192
	v_add_f32_e32 v0, v236, v237
	v_cvt_pk_bf16_f32 v236, v236, v237
	v_exp_f32_e32 v240, v240
	v_cndmask_b32_e64 v239, 0, v239, s[20:21]
	s_waitcnt lgkmcnt(1)
	v_mfma_f32_32x32x16_bf16 v[80:95], v[2:5], v[148:151], v[80:95]
	ds_read_b128 v[10:13], v217 offset:8192
	v_add_f32_e32 v0, v238, v0
	v_exp_f32_e32 v241, v241
	v_cndmask_b32_e64 v240, 0, v240, s[46:47]
	v_add_f32_e32 v0, v239, v0
	s_waitcnt lgkmcnt(1)
	v_mfma_f32_32x32x16_bf16 v[144:159], v[6:9], v[160:163], 0
	ds_read_b128 v[2:5], v222 offset:8192
	v_cvt_pk_bf16_f32 v237, v238, v239
	v_exp_f32_e32 v242, v242
	v_cndmask_b32_e64 v241, 0, v241, s[48:49]
	v_add_f32_e32 v0, v240, v0
	s_waitcnt lgkmcnt(1)
	v_mfma_f32_32x32x16_bf16 v[144:159], v[10:13], v[164:167], v[144:159]
	ds_read_b128 v[6:9], v223 offset:8192
	v_exp_f32_e32 v243, v243
	v_cndmask_b32_e64 v242, 0, v242, s[50:51]
	v_add_f32_e32 v0, v241, v0
	v_cvt_pk_bf16_f32 v238, v240, v241
	s_waitcnt lgkmcnt(1)
	v_mfma_f32_32x32x16_bf16 v[144:159], v[2:5], v[168:171], v[144:159]
	ds_read_b128 v[10:13], v15 offset:32768
	v_exp_f32_e32 v244, v244
	v_cndmask_b32_e64 v243, 0, v243, s[76:77]
	v_add_f32_e32 v0, v242, v0
	v_exp_f32_e32 v245, v245
	s_waitcnt lgkmcnt(1)
	v_mfma_f32_32x32x16_bf16 v[144:159], v[6:9], v[172:175], v[144:159]
	ds_read_b128 v[2:5], v15 offset:40960
	v_cndmask_b32_e64 v244, 0, v244, s[84:85]
	v_add_f32_e32 v0, v243, v0
	v_cvt_pk_bf16_f32 v239, v242, v243
	v_exp_f32_e32 v246, v246
	s_waitcnt lgkmcnt(1)
	v_mfma_f32_32x32x16_bf16 v[64:79], v[10:13], v[236:239], v[64:79]
	ds_read_b128 v[6:9], v15 offset:49152
	v_cndmask_b32_e64 v245, 0, v245, s[86:87]
	v_add_f32_e32 v0, v244, v0
	v_exp_f32_e32 v247, v247
	v_cndmask_b32_e64 v246, 0, v246, s[88:89]
	s_waitcnt lgkmcnt(1)
	v_mfma_f32_32x32x16_bf16 v[48:63], v[2:5], v[236:239], v[48:63]
	ds_read_b128 v[10:13], v15 offset:57344
	v_add_f32_e32 v0, v245, v0
	v_cvt_pk_bf16_f32 v240, v244, v245
	v_exp_f32_e32 v248, v248
	v_cndmask_b32_e64 v247, 0, v247, s[90:91]
	s_waitcnt lgkmcnt(1)
	v_mfma_f32_32x32x16_bf16 v[32:47], v[6:9], v[236:239], v[32:47]
	v_xor_b32_e32 v253, 32, v15
	ds_read_b128 v[2:5], v253 offset:32768
	v_add_f32_e32 v0, v246, v0
	v_exp_f32_e32 v249, v249
	v_cndmask_b32_e64 v248, 0, v248, s[92:93]
	v_add_f32_e32 v0, v247, v0
	s_waitcnt lgkmcnt(1)
	v_mfma_f32_32x32x16_bf16 v[16:31], v[10:13], v[236:239], v[16:31]
	ds_read_b128 v[6:9], v253 offset:40960
	v_cvt_pk_bf16_f32 v241, v246, v247
	v_exp_f32_e32 v250, v250
	v_cndmask_b32_e64 v249, 0, v249, s[94:95]
	v_add_f32_e32 v0, v248, v0
	v_exp_f32_e32 v251, v251
	v_cndmask_b32_e64 v250, 0, v250, s[96:97]
	v_add_f32_e32 v0, v249, v0
	v_cvt_pk_bf16_f32 v242, v248, v249
	v_cndmask_b32_e64 v251, 0, v251, vcc
	v_add_f32_e32 v0, v250, v0
	v_add_f32_e32 v0, v251, v0
	v_cvt_pk_bf16_f32 v243, v250, v251
	s_waitcnt lgkmcnt(1)
	s_nop 0
	v_mfma_f32_32x32x16_bf16 v[64:79], v[2:5], v[240:243], v[64:79]
	ds_read_b128 v[10:13], v253 offset:49152
	v_add_f32_e32 v196, v196, v0
	v_subrev_u32_e32 v219, 32, v218
	v_cmp_ge_i32_e64 s[4:5], v219, 0
	v_cmp_ge_i32_e64 s[6:7], v219, 1
	s_waitcnt lgkmcnt(1)
	v_mfma_f32_32x32x16_bf16 v[48:63], v[6:9], v[240:243], v[48:63]
	ds_read_b128 v[2:5], v253 offset:57344
	v_cmp_ge_i32_e64 s[10:11], v219, 2
	v_cmp_ge_i32_e64 s[20:21], v219, 3
	v_cmp_ge_i32_e64 s[46:47], v219, 4
	v_cmp_ge_i32_e64 s[48:49], v219, 5
	s_waitcnt lgkmcnt(1)
	v_mfma_f32_32x32x16_bf16 v[32:47], v[10:13], v[240:243], v[32:47]
	ds_read_b128 v[6:9], v225 offset:8192
	v_cmp_ge_i32_e64 s[50:51], v219, 6
	v_cmp_ge_i32_e64 s[76:77], v219, 7
	v_cmp_ge_i32_e64 s[84:85], v219, 16
	v_cmp_ge_i32_e64 s[86:87], v219, 17
	s_waitcnt lgkmcnt(1)
	v_mfma_f32_32x32x16_bf16 v[16:31], v[2:5], v[240:243], v[16:31]
	ds_read_b128 v[10:13], v230 offset:8192
	v_cmp_ge_i32_e64 s[88:89], v219, 18
	v_cmp_ge_i32_e64 s[90:91], v219, 19
	v_cmp_ge_i32_e64 s[92:93], v219, 20
	v_cmp_ge_i32_e64 s[94:95], v219, 21
	s_waitcnt lgkmcnt(1)
	v_mfma_f32_32x32x16_bf16 v[236:251], v[6:9], v[176:179], 0
	ds_read_b128 v[2:5], v231 offset:8192
	v_cmp_ge_i32_e64 s[96:97], v219, 22
	v_cmp_ge_i32_e64 vcc, v219, 23
	v_exp_f32_e32 v144, v144
	v_exp_f32_e32 v145, v145
	s_waitcnt lgkmcnt(1)
	v_mfma_f32_32x32x16_bf16 v[236:251], v[10:13], v[180:183], v[236:251]
	ds_read_b128 v[6:9], v235 offset:8192
	v_cndmask_b32_e64 v144, 0, v144, s[4:5]
	v_exp_f32_e32 v146, v146
	v_cndmask_b32_e64 v145, 0, v145, s[6:7]
	v_exp_f32_e32 v147, v147
	s_waitcnt lgkmcnt(1)
	v_mfma_f32_32x32x16_bf16 v[236:251], v[2:5], v[184:187], v[236:251]
	v_xor_b32_e32 v252, 64, v15
	ds_read_b128 v[10:13], v252 offset:32768
	v_cndmask_b32_e64 v146, 0, v146, s[10:11]
	v_add_f32_e32 v0, v144, v145
	v_cvt_pk_bf16_f32 v144, v144, v145
	v_exp_f32_e32 v148, v148
	s_waitcnt lgkmcnt(1)
	v_mfma_f32_32x32x16_bf16 v[236:251], v[6:9], v[188:191], v[236:251]
	ds_read_b128 v[2:5], v252 offset:40960
	v_cndmask_b32_e64 v147, 0, v147, s[20:21]
	v_add_f32_e32 v0, v146, v0
	v_exp_f32_e32 v149, v149
	v_cndmask_b32_e64 v148, 0, v148, s[46:47]
	v_add_f32_e32 v0, v147, v0
	v_cvt_pk_bf16_f32 v145, v146, v147
	v_exp_f32_e32 v150, v150
	v_cndmask_b32_e64 v149, 0, v149, s[48:49]
	v_add_f32_e32 v0, v148, v0
	v_exp_f32_e32 v151, v151
	v_cndmask_b32_e64 v150, 0, v150, s[50:51]
	v_add_f32_e32 v0, v149, v0
	v_cvt_pk_bf16_f32 v146, v148, v149
	v_exp_f32_e32 v152, v152
	v_cndmask_b32_e64 v151, 0, v151, s[76:77]
	v_add_f32_e32 v0, v150, v0
	v_exp_f32_e32 v153, v153
	v_cndmask_b32_e64 v152, 0, v152, s[84:85]
	v_add_f32_e32 v0, v151, v0
	v_cvt_pk_bf16_f32 v147, v150, v151
	s_waitcnt lgkmcnt(1)
	s_nop 0
	v_mfma_f32_32x32x16_bf16 v[128:143], v[10:13], v[144:147], v[128:143]
	ds_read_b128 v[6:9], v252 offset:49152
	v_exp_f32_e32 v154, v154
	v_cndmask_b32_e64 v153, 0, v153, s[86:87]
	v_add_f32_e32 v0, v152, v0
	v_exp_f32_e32 v155, v155
	s_waitcnt lgkmcnt(1)
	v_mfma_f32_32x32x16_bf16 v[112:127], v[2:5], v[144:147], v[112:127]
	ds_read_b128 v[10:13], v252 offset:57344
	v_cndmask_b32_e64 v154, 0, v154, s[88:89]
	v_add_f32_e32 v0, v153, v0
	v_cvt_pk_bf16_f32 v148, v152, v153
	v_exp_f32_e32 v156, v156
	s_waitcnt lgkmcnt(1)
	v_mfma_f32_32x32x16_bf16 v[96:111], v[6:9], v[144:147], v[96:111]
	v_xor_b32_e32 v253, 0x60, v15
	ds_read_b128 v[2:5], v253 offset:32768
	v_cndmask_b32_e64 v155, 0, v155, s[90:91]
	v_add_f32_e32 v0, v154, v0
	v_exp_f32_e32 v157, v157
	v_cndmask_b32_e64 v156, 0, v156, s[92:93]
	s_waitcnt lgkmcnt(1)
	v_mfma_f32_32x32x16_bf16 v[80:95], v[10:13], v[144:147], v[80:95]
	ds_read_b128 v[6:9], v253 offset:40960
	v_add_f32_e32 v0, v155, v0
	v_cvt_pk_bf16_f32 v149, v154, v155
	v_exp_f32_e32 v158, v158
	v_cndmask_b32_e64 v157, 0, v157, s[94:95]
	v_add_f32_e32 v0, v156, v0
	v_exp_f32_e32 v159, v159
	v_cndmask_b32_e64 v158, 0, v158, s[96:97]
	v_add_f32_e32 v0, v157, v0
	v_cvt_pk_bf16_f32 v150, v156, v157
	v_cndmask_b32_e64 v159, 0, v159, vcc
	v_add_f32_e32 v0, v158, v0
	v_add_f32_e32 v0, v159, v0
	v_cvt_pk_bf16_f32 v151, v158, v159
	s_waitcnt lgkmcnt(1)
	s_nop 0
	v_mfma_f32_32x32x16_bf16 v[128:143], v[2:5], v[148:151], v[128:143]
	ds_read_b128 v[10:13], v253 offset:49152
	v_add_f32_e32 v197, v197, v0
	v_exp_f32_e32 v236, v236
	v_exp_f32_e32 v237, v237
	v_cndmask_b32_e64 v236, 0, v236, s[4:5]
	s_waitcnt lgkmcnt(1)
	v_mfma_f32_32x32x16_bf16 v[112:127], v[6:9], v[148:151], v[112:127]
	ds_read_b128 v[2:5], v253 offset:57344
	v_exp_f32_e32 v238, v238
	v_cndmask_b32_e64 v237, 0, v237, s[6:7]
	v_exp_f32_e32 v239, v239
	v_cndmask_b32_e64 v238, 0, v238, s[10:11]
	s_waitcnt lgkmcnt(1)
	v_mfma_f32_32x32x16_bf16 v[96:111], v[10:13], v[148:151], v[96:111]
	ds_read_b128 v[6:9], v14 offset:16384
	v_add_f32_e32 v0, v236, v237
	v_cvt_pk_bf16_f32 v236, v236, v237
	v_exp_f32_e32 v240, v240
	v_cndmask_b32_e64 v239, 0, v239, s[20:21]
	s_waitcnt lgkmcnt(1)
	v_mfma_f32_32x32x16_bf16 v[80:95], v[2:5], v[148:151], v[80:95]
	ds_read_b128 v[10:13], v217 offset:16384
	v_add_f32_e32 v0, v238, v0
	v_exp_f32_e32 v241, v241
	v_cndmask_b32_e64 v240, 0, v240, s[46:47]
	v_add_f32_e32 v0, v239, v0
	s_waitcnt lgkmcnt(1)
	v_mfma_f32_32x32x16_bf16 v[144:159], v[6:9], v[160:163], 0
	ds_read_b128 v[2:5], v222 offset:16384
	v_cvt_pk_bf16_f32 v237, v238, v239
	v_exp_f32_e32 v242, v242
	v_cndmask_b32_e64 v241, 0, v241, s[48:49]
	v_add_f32_e32 v0, v240, v0
	s_waitcnt lgkmcnt(1)
	v_mfma_f32_32x32x16_bf16 v[144:159], v[10:13], v[164:167], v[144:159]
	ds_read_b128 v[6:9], v223 offset:16384
	v_exp_f32_e32 v243, v243
	v_cndmask_b32_e64 v242, 0, v242, s[50:51]
	v_add_f32_e32 v0, v241, v0
	v_cvt_pk_bf16_f32 v238, v240, v241
	s_waitcnt lgkmcnt(1)
	v_mfma_f32_32x32x16_bf16 v[144:159], v[2:5], v[168:171], v[144:159]
	v_xor_b32_e32 v252, 64, v15
	ds_read_b128 v[10:13], v252 offset:32768
	v_exp_f32_e32 v244, v244
	v_cndmask_b32_e64 v243, 0, v243, s[76:77]
	v_add_f32_e32 v0, v242, v0
	v_exp_f32_e32 v245, v245
	s_waitcnt lgkmcnt(1)
	v_mfma_f32_32x32x16_bf16 v[144:159], v[6:9], v[172:175], v[144:159]
	ds_read_b128 v[2:5], v252 offset:40960
	v_cndmask_b32_e64 v244, 0, v244, s[84:85]
	v_add_f32_e32 v0, v243, v0
	v_cvt_pk_bf16_f32 v239, v242, v243
	v_exp_f32_e32 v246, v246
	s_waitcnt lgkmcnt(1)
	v_mfma_f32_32x32x16_bf16 v[64:79], v[10:13], v[236:239], v[64:79]
	ds_read_b128 v[6:9], v252 offset:49152
	v_cndmask_b32_e64 v245, 0, v245, s[86:87]
	v_add_f32_e32 v0, v244, v0
	v_exp_f32_e32 v247, v247
	v_cndmask_b32_e64 v246, 0, v246, s[88:89]
	s_waitcnt lgkmcnt(1)
	v_mfma_f32_32x32x16_bf16 v[48:63], v[2:5], v[236:239], v[48:63]
	ds_read_b128 v[10:13], v252 offset:57344
	v_add_f32_e32 v0, v245, v0
	v_cvt_pk_bf16_f32 v240, v244, v245
	v_exp_f32_e32 v248, v248
	v_cndmask_b32_e64 v247, 0, v247, s[90:91]
	s_waitcnt lgkmcnt(1)
	v_mfma_f32_32x32x16_bf16 v[32:47], v[6:9], v[236:239], v[32:47]
	v_xor_b32_e32 v253, 0x60, v15
	ds_read_b128 v[2:5], v253 offset:32768
	v_add_f32_e32 v0, v246, v0
	v_exp_f32_e32 v249, v249
	v_cndmask_b32_e64 v248, 0, v248, s[92:93]
	v_add_f32_e32 v0, v247, v0
	s_waitcnt lgkmcnt(1)
	v_mfma_f32_32x32x16_bf16 v[16:31], v[10:13], v[236:239], v[16:31]
	ds_read_b128 v[6:9], v253 offset:40960
	v_cvt_pk_bf16_f32 v241, v246, v247
	v_exp_f32_e32 v250, v250
	v_cndmask_b32_e64 v249, 0, v249, s[94:95]
	v_add_f32_e32 v0, v248, v0
	v_exp_f32_e32 v251, v251
	v_cndmask_b32_e64 v250, 0, v250, s[96:97]
	v_add_f32_e32 v0, v249, v0
	v_cvt_pk_bf16_f32 v242, v248, v249
	v_cndmask_b32_e64 v251, 0, v251, vcc
	v_add_f32_e32 v0, v250, v0
	v_add_f32_e32 v0, v251, v0
	v_cvt_pk_bf16_f32 v243, v250, v251
	s_waitcnt lgkmcnt(1)
	s_nop 0
	v_mfma_f32_32x32x16_bf16 v[64:79], v[2:5], v[240:243], v[64:79]
	ds_read_b128 v[10:13], v253 offset:49152
	v_add_f32_e32 v196, v196, v0
	v_subrev_u32_e32 v219, 64, v218
	v_cmp_ge_i32_e64 s[4:5], v219, 0
	v_cmp_ge_i32_e64 s[6:7], v219, 1
	s_waitcnt lgkmcnt(1)
	v_mfma_f32_32x32x16_bf16 v[48:63], v[6:9], v[240:243], v[48:63]
	ds_read_b128 v[2:5], v253 offset:57344
	v_cmp_ge_i32_e64 s[10:11], v219, 2
	v_cmp_ge_i32_e64 s[20:21], v219, 3
	v_cmp_ge_i32_e64 s[46:47], v219, 4
	v_cmp_ge_i32_e64 s[48:49], v219, 5
	s_waitcnt lgkmcnt(1)
	v_mfma_f32_32x32x16_bf16 v[32:47], v[10:13], v[240:243], v[32:47]
	ds_read_b128 v[6:9], v225 offset:16384
	v_cmp_ge_i32_e64 s[50:51], v219, 6
	v_cmp_ge_i32_e64 s[76:77], v219, 7
	v_cmp_ge_i32_e64 s[84:85], v219, 16
	v_cmp_ge_i32_e64 s[86:87], v219, 17
	s_waitcnt lgkmcnt(1)
	v_mfma_f32_32x32x16_bf16 v[16:31], v[2:5], v[240:243], v[16:31]
	ds_read_b128 v[10:13], v230 offset:16384
	v_cmp_ge_i32_e64 s[88:89], v219, 18
	v_cmp_ge_i32_e64 s[90:91], v219, 19
	v_cmp_ge_i32_e64 s[92:93], v219, 20
	v_cmp_ge_i32_e64 s[94:95], v219, 21
	s_waitcnt lgkmcnt(1)
	v_mfma_f32_32x32x16_bf16 v[236:251], v[6:9], v[176:179], 0
	ds_read_b128 v[2:5], v231 offset:16384
	v_cmp_ge_i32_e64 s[96:97], v219, 22
	v_cmp_ge_i32_e64 vcc, v219, 23
	v_exp_f32_e32 v144, v144
	v_exp_f32_e32 v145, v145
	s_waitcnt lgkmcnt(1)
	v_mfma_f32_32x32x16_bf16 v[236:251], v[10:13], v[180:183], v[236:251]
	ds_read_b128 v[6:9], v235 offset:16384
	v_cndmask_b32_e64 v144, 0, v144, s[4:5]
	v_exp_f32_e32 v146, v146
	v_cndmask_b32_e64 v145, 0, v145, s[6:7]
	v_exp_f32_e32 v147, v147
	s_waitcnt lgkmcnt(1)
	v_mfma_f32_32x32x16_bf16 v[236:251], v[2:5], v[184:187], v[236:251]
	v_xor_b32_e32 v252, 0x80, v15
	ds_read_b128 v[10:13], v252 offset:32768
	v_cndmask_b32_e64 v146, 0, v146, s[10:11]
	v_add_f32_e32 v0, v144, v145
	v_cvt_pk_bf16_f32 v144, v144, v145
	v_exp_f32_e32 v148, v148
	s_waitcnt lgkmcnt(1)
	v_mfma_f32_32x32x16_bf16 v[236:251], v[6:9], v[188:191], v[236:251]
	ds_read_b128 v[2:5], v252 offset:40960
	v_cndmask_b32_e64 v147, 0, v147, s[20:21]
	v_add_f32_e32 v0, v146, v0
	v_exp_f32_e32 v149, v149
	v_cndmask_b32_e64 v148, 0, v148, s[46:47]
	v_add_f32_e32 v0, v147, v0
	v_cvt_pk_bf16_f32 v145, v146, v147
	v_exp_f32_e32 v150, v150
	v_cndmask_b32_e64 v149, 0, v149, s[48:49]
	v_add_f32_e32 v0, v148, v0
	v_exp_f32_e32 v151, v151
	v_cndmask_b32_e64 v150, 0, v150, s[50:51]
	v_add_f32_e32 v0, v149, v0
	v_cvt_pk_bf16_f32 v146, v148, v149
	v_exp_f32_e32 v152, v152
	v_cndmask_b32_e64 v151, 0, v151, s[76:77]
	v_add_f32_e32 v0, v150, v0
	v_exp_f32_e32 v153, v153
	v_cndmask_b32_e64 v152, 0, v152, s[84:85]
	v_add_f32_e32 v0, v151, v0
	v_cvt_pk_bf16_f32 v147, v150, v151
	s_waitcnt lgkmcnt(1)
	s_nop 0
	v_mfma_f32_32x32x16_bf16 v[128:143], v[10:13], v[144:147], v[128:143]
	ds_read_b128 v[6:9], v252 offset:49152
	v_exp_f32_e32 v154, v154
	v_cndmask_b32_e64 v153, 0, v153, s[86:87]
	v_add_f32_e32 v0, v152, v0
	v_exp_f32_e32 v155, v155
	s_waitcnt lgkmcnt(1)
	v_mfma_f32_32x32x16_bf16 v[112:127], v[2:5], v[144:147], v[112:127]
	ds_read_b128 v[10:13], v252 offset:57344
	v_cndmask_b32_e64 v154, 0, v154, s[88:89]
	v_add_f32_e32 v0, v153, v0
	v_cvt_pk_bf16_f32 v148, v152, v153
	v_exp_f32_e32 v156, v156
	s_waitcnt lgkmcnt(1)
	v_mfma_f32_32x32x16_bf16 v[96:111], v[6:9], v[144:147], v[96:111]
	v_xor_b32_e32 v253, 0xa0, v15
	ds_read_b128 v[2:5], v253 offset:32768
	v_cndmask_b32_e64 v155, 0, v155, s[90:91]
	v_add_f32_e32 v0, v154, v0
	v_exp_f32_e32 v157, v157
	v_cndmask_b32_e64 v156, 0, v156, s[92:93]
	s_waitcnt lgkmcnt(1)
	v_mfma_f32_32x32x16_bf16 v[80:95], v[10:13], v[144:147], v[80:95]
	ds_read_b128 v[6:9], v253 offset:40960
	v_add_f32_e32 v0, v155, v0
	v_cvt_pk_bf16_f32 v149, v154, v155
	v_exp_f32_e32 v158, v158
	v_cndmask_b32_e64 v157, 0, v157, s[94:95]
	v_add_f32_e32 v0, v156, v0
	v_exp_f32_e32 v159, v159
	v_cndmask_b32_e64 v158, 0, v158, s[96:97]
	v_add_f32_e32 v0, v157, v0
	v_cvt_pk_bf16_f32 v150, v156, v157
	v_cndmask_b32_e64 v159, 0, v159, vcc
	v_add_f32_e32 v0, v158, v0
	v_add_f32_e32 v0, v159, v0
	v_cvt_pk_bf16_f32 v151, v158, v159
	s_waitcnt lgkmcnt(1)
	s_nop 0
	v_mfma_f32_32x32x16_bf16 v[128:143], v[2:5], v[148:151], v[128:143]
	ds_read_b128 v[10:13], v253 offset:49152
	v_add_f32_e32 v197, v197, v0
	v_exp_f32_e32 v236, v236
	v_exp_f32_e32 v237, v237
	v_cndmask_b32_e64 v236, 0, v236, s[4:5]
	s_waitcnt lgkmcnt(1)
	v_mfma_f32_32x32x16_bf16 v[112:127], v[6:9], v[148:151], v[112:127]
	ds_read_b128 v[2:5], v253 offset:57344
	v_exp_f32_e32 v238, v238
	v_cndmask_b32_e64 v237, 0, v237, s[6:7]
	v_exp_f32_e32 v239, v239
	v_cndmask_b32_e64 v238, 0, v238, s[10:11]
	s_waitcnt lgkmcnt(1)
	v_mfma_f32_32x32x16_bf16 v[96:111], v[10:13], v[148:151], v[96:111]
	ds_read_b128 v[6:9], v14 offset:24576
	v_add_f32_e32 v0, v236, v237
	v_cvt_pk_bf16_f32 v236, v236, v237
	v_exp_f32_e32 v240, v240
	v_cndmask_b32_e64 v239, 0, v239, s[20:21]
	s_waitcnt lgkmcnt(1)
	v_mfma_f32_32x32x16_bf16 v[80:95], v[2:5], v[148:151], v[80:95]
	ds_read_b128 v[10:13], v217 offset:24576
	v_add_f32_e32 v0, v238, v0
	v_exp_f32_e32 v241, v241
	v_cndmask_b32_e64 v240, 0, v240, s[46:47]
	v_add_f32_e32 v0, v239, v0
	s_waitcnt lgkmcnt(1)
	v_mfma_f32_32x32x16_bf16 v[144:159], v[6:9], v[160:163], 0
	ds_read_b128 v[2:5], v222 offset:24576
	v_cvt_pk_bf16_f32 v237, v238, v239
	v_exp_f32_e32 v242, v242
	v_cndmask_b32_e64 v241, 0, v241, s[48:49]
	v_add_f32_e32 v0, v240, v0
	s_waitcnt lgkmcnt(1)
	v_mfma_f32_32x32x16_bf16 v[144:159], v[10:13], v[164:167], v[144:159]
	ds_read_b128 v[6:9], v223 offset:24576
	v_exp_f32_e32 v243, v243
	v_cndmask_b32_e64 v242, 0, v242, s[50:51]
	v_add_f32_e32 v0, v241, v0
	v_cvt_pk_bf16_f32 v238, v240, v241
	s_waitcnt lgkmcnt(1)
	v_mfma_f32_32x32x16_bf16 v[144:159], v[2:5], v[168:171], v[144:159]
	v_xor_b32_e32 v252, 0x80, v15
	ds_read_b128 v[10:13], v252 offset:32768
	v_exp_f32_e32 v244, v244
	v_cndmask_b32_e64 v243, 0, v243, s[76:77]
	v_add_f32_e32 v0, v242, v0
	v_exp_f32_e32 v245, v245
	s_waitcnt lgkmcnt(1)
	v_mfma_f32_32x32x16_bf16 v[144:159], v[6:9], v[172:175], v[144:159]
	ds_read_b128 v[2:5], v252 offset:40960
	v_cndmask_b32_e64 v244, 0, v244, s[84:85]
	v_add_f32_e32 v0, v243, v0
	v_cvt_pk_bf16_f32 v239, v242, v243
	v_exp_f32_e32 v246, v246
	s_waitcnt lgkmcnt(1)
	v_mfma_f32_32x32x16_bf16 v[64:79], v[10:13], v[236:239], v[64:79]
	ds_read_b128 v[6:9], v252 offset:49152
	v_cndmask_b32_e64 v245, 0, v245, s[86:87]
	v_add_f32_e32 v0, v244, v0
	v_exp_f32_e32 v247, v247
	v_cndmask_b32_e64 v246, 0, v246, s[88:89]
	s_waitcnt lgkmcnt(1)
	v_mfma_f32_32x32x16_bf16 v[48:63], v[2:5], v[236:239], v[48:63]
	ds_read_b128 v[10:13], v252 offset:57344
	v_add_f32_e32 v0, v245, v0
	v_cvt_pk_bf16_f32 v240, v244, v245
	v_exp_f32_e32 v248, v248
	v_cndmask_b32_e64 v247, 0, v247, s[90:91]
	s_waitcnt lgkmcnt(1)
	v_mfma_f32_32x32x16_bf16 v[32:47], v[6:9], v[236:239], v[32:47]
	v_xor_b32_e32 v253, 0xa0, v15
	ds_read_b128 v[2:5], v253 offset:32768
	v_add_f32_e32 v0, v246, v0
	v_exp_f32_e32 v249, v249
	v_cndmask_b32_e64 v248, 0, v248, s[92:93]
	v_add_f32_e32 v0, v247, v0
	s_waitcnt lgkmcnt(1)
	v_mfma_f32_32x32x16_bf16 v[16:31], v[10:13], v[236:239], v[16:31]
	ds_read_b128 v[6:9], v253 offset:40960
	v_cvt_pk_bf16_f32 v241, v246, v247
	v_exp_f32_e32 v250, v250
	v_cndmask_b32_e64 v249, 0, v249, s[94:95]
	v_add_f32_e32 v0, v248, v0
	v_exp_f32_e32 v251, v251
	v_cndmask_b32_e64 v250, 0, v250, s[96:97]
	v_add_f32_e32 v0, v249, v0
	v_cvt_pk_bf16_f32 v242, v248, v249
	v_cndmask_b32_e64 v251, 0, v251, vcc
	v_add_f32_e32 v0, v250, v0
	v_add_f32_e32 v0, v251, v0
	v_cvt_pk_bf16_f32 v243, v250, v251
	s_waitcnt lgkmcnt(1)
	s_nop 0
	v_mfma_f32_32x32x16_bf16 v[64:79], v[2:5], v[240:243], v[64:79]
	ds_read_b128 v[10:13], v253 offset:49152
	v_add_f32_e32 v196, v196, v0
	v_subrev_u32_e32 v219, 0x60, v218
	v_cmp_ge_i32_e64 s[4:5], v219, 0
	v_cmp_ge_i32_e64 s[6:7], v219, 1
	s_waitcnt lgkmcnt(1)
	v_mfma_f32_32x32x16_bf16 v[48:63], v[6:9], v[240:243], v[48:63]
	ds_read_b128 v[2:5], v253 offset:57344
	v_cmp_ge_i32_e64 s[10:11], v219, 2
	v_cmp_ge_i32_e64 s[20:21], v219, 3
	v_cmp_ge_i32_e64 s[46:47], v219, 4
	v_cmp_ge_i32_e64 s[48:49], v219, 5
	s_waitcnt lgkmcnt(1)
	v_mfma_f32_32x32x16_bf16 v[32:47], v[10:13], v[240:243], v[32:47]
	ds_read_b128 v[6:9], v225 offset:24576
	v_cmp_ge_i32_e64 s[50:51], v219, 6
	v_cmp_ge_i32_e64 s[76:77], v219, 7
	v_cmp_ge_i32_e64 s[84:85], v219, 16
	v_cmp_ge_i32_e64 s[86:87], v219, 17
	s_waitcnt lgkmcnt(1)
	v_mfma_f32_32x32x16_bf16 v[16:31], v[2:5], v[240:243], v[16:31]
	ds_read_b128 v[10:13], v230 offset:24576
	v_cmp_ge_i32_e64 s[88:89], v219, 18
	v_cmp_ge_i32_e64 s[90:91], v219, 19
	v_cmp_ge_i32_e64 s[92:93], v219, 20
	v_cmp_ge_i32_e64 s[94:95], v219, 21
	s_waitcnt lgkmcnt(1)
	v_mfma_f32_32x32x16_bf16 v[236:251], v[6:9], v[176:179], 0
	ds_read_b128 v[2:5], v231 offset:24576
	v_cmp_ge_i32_e64 s[96:97], v219, 22
	v_cmp_ge_i32_e64 vcc, v219, 23
	v_exp_f32_e32 v144, v144
	v_exp_f32_e32 v145, v145
	s_waitcnt lgkmcnt(1)
	v_mfma_f32_32x32x16_bf16 v[236:251], v[10:13], v[180:183], v[236:251]
	ds_read_b128 v[6:9], v235 offset:24576
	v_cndmask_b32_e64 v144, 0, v144, s[4:5]
	v_exp_f32_e32 v146, v146
	v_cndmask_b32_e64 v145, 0, v145, s[6:7]
	v_exp_f32_e32 v147, v147
	s_waitcnt lgkmcnt(1)
	v_mfma_f32_32x32x16_bf16 v[236:251], v[2:5], v[184:187], v[236:251]
	v_xor_b32_e32 v252, 0xc0, v15
	ds_read_b128 v[10:13], v252 offset:32768
	v_cndmask_b32_e64 v146, 0, v146, s[10:11]
	v_add_f32_e32 v0, v144, v145
	v_cvt_pk_bf16_f32 v144, v144, v145
	v_exp_f32_e32 v148, v148
	s_waitcnt lgkmcnt(1)
	v_mfma_f32_32x32x16_bf16 v[236:251], v[6:9], v[188:191], v[236:251]
	ds_read_b128 v[2:5], v252 offset:40960
	v_cndmask_b32_e64 v147, 0, v147, s[20:21]
	v_add_f32_e32 v0, v146, v0
	v_exp_f32_e32 v149, v149
	v_cndmask_b32_e64 v148, 0, v148, s[46:47]
	v_add_f32_e32 v0, v147, v0
	v_cvt_pk_bf16_f32 v145, v146, v147
	v_exp_f32_e32 v150, v150
	v_cndmask_b32_e64 v149, 0, v149, s[48:49]
	v_add_f32_e32 v0, v148, v0
	v_exp_f32_e32 v151, v151
	v_cndmask_b32_e64 v150, 0, v150, s[50:51]
	v_add_f32_e32 v0, v149, v0
	v_cvt_pk_bf16_f32 v146, v148, v149
	v_exp_f32_e32 v152, v152
	v_cndmask_b32_e64 v151, 0, v151, s[76:77]
	v_add_f32_e32 v0, v150, v0
	v_exp_f32_e32 v153, v153
	v_cndmask_b32_e64 v152, 0, v152, s[84:85]
	v_add_f32_e32 v0, v151, v0
	v_cvt_pk_bf16_f32 v147, v150, v151
	s_waitcnt lgkmcnt(1)
	s_nop 0
	v_mfma_f32_32x32x16_bf16 v[128:143], v[10:13], v[144:147], v[128:143]
	ds_read_b128 v[6:9], v252 offset:49152
	v_exp_f32_e32 v154, v154
	v_cndmask_b32_e64 v153, 0, v153, s[86:87]
	v_add_f32_e32 v0, v152, v0
	v_exp_f32_e32 v155, v155
	s_waitcnt lgkmcnt(1)
	v_mfma_f32_32x32x16_bf16 v[112:127], v[2:5], v[144:147], v[112:127]
	ds_read_b128 v[10:13], v252 offset:57344
	v_cndmask_b32_e64 v154, 0, v154, s[88:89]
	v_add_f32_e32 v0, v153, v0
	v_cvt_pk_bf16_f32 v148, v152, v153
	v_exp_f32_e32 v156, v156
	s_waitcnt lgkmcnt(1)
	v_mfma_f32_32x32x16_bf16 v[96:111], v[6:9], v[144:147], v[96:111]
	v_xor_b32_e32 v253, 0xe0, v15
	ds_read_b128 v[2:5], v253 offset:32768
	v_cndmask_b32_e64 v155, 0, v155, s[90:91]
	v_add_f32_e32 v0, v154, v0
	v_exp_f32_e32 v157, v157
	v_cndmask_b32_e64 v156, 0, v156, s[92:93]
	s_waitcnt lgkmcnt(1)
	v_mfma_f32_32x32x16_bf16 v[80:95], v[10:13], v[144:147], v[80:95]
	ds_read_b128 v[6:9], v253 offset:40960
	v_add_f32_e32 v0, v155, v0
	v_cvt_pk_bf16_f32 v149, v154, v155
	v_exp_f32_e32 v158, v158
	v_cndmask_b32_e64 v157, 0, v157, s[94:95]
	v_add_f32_e32 v0, v156, v0
	v_exp_f32_e32 v159, v159
	v_cndmask_b32_e64 v158, 0, v158, s[96:97]
	v_add_f32_e32 v0, v157, v0
	v_cvt_pk_bf16_f32 v150, v156, v157
	v_cndmask_b32_e64 v159, 0, v159, vcc
	v_add_f32_e32 v0, v158, v0
	v_add_f32_e32 v0, v159, v0
	v_cvt_pk_bf16_f32 v151, v158, v159
	s_waitcnt lgkmcnt(1)
	s_nop 0
	v_mfma_f32_32x32x16_bf16 v[128:143], v[2:5], v[148:151], v[128:143]
	ds_read_b128 v[10:13], v253 offset:49152
	v_add_f32_e32 v197, v197, v0
	v_exp_f32_e32 v236, v236
	v_exp_f32_e32 v237, v237
	v_cndmask_b32_e64 v236, 0, v236, s[4:5]
	s_waitcnt lgkmcnt(1)
	v_mfma_f32_32x32x16_bf16 v[112:127], v[6:9], v[148:151], v[112:127]
	ds_read_b128 v[2:5], v253 offset:57344
	v_exp_f32_e32 v238, v238
	v_cndmask_b32_e64 v237, 0, v237, s[6:7]
	v_exp_f32_e32 v239, v239
	v_cndmask_b32_e64 v238, 0, v238, s[10:11]
	s_waitcnt lgkmcnt(1)
	v_mfma_f32_32x32x16_bf16 v[96:111], v[10:13], v[148:151], v[96:111]
	v_xor_b32_e32 v252, 0xc0, v15
	ds_read_b128 v[6:9], v252 offset:32768
	v_add_f32_e32 v0, v236, v237
	v_cvt_pk_bf16_f32 v236, v236, v237
	v_exp_f32_e32 v240, v240
	v_cndmask_b32_e64 v239, 0, v239, s[20:21]
	s_waitcnt lgkmcnt(1)
	v_mfma_f32_32x32x16_bf16 v[80:95], v[2:5], v[148:151], v[80:95]
	ds_read_b128 v[10:13], v252 offset:40960
	v_add_f32_e32 v0, v238, v0
	v_exp_f32_e32 v241, v241
	v_cndmask_b32_e64 v240, 0, v240, s[46:47]
	v_add_f32_e32 v0, v239, v0
	v_cvt_pk_bf16_f32 v237, v238, v239
	v_exp_f32_e32 v242, v242
	v_cndmask_b32_e64 v241, 0, v241, s[48:49]
	v_add_f32_e32 v0, v240, v0
	v_exp_f32_e32 v243, v243
	v_cndmask_b32_e64 v242, 0, v242, s[50:51]
	v_add_f32_e32 v0, v241, v0
	v_cvt_pk_bf16_f32 v238, v240, v241
	v_exp_f32_e32 v244, v244
	v_cndmask_b32_e64 v243, 0, v243, s[76:77]
	v_add_f32_e32 v0, v242, v0
	v_exp_f32_e32 v245, v245
	v_cndmask_b32_e64 v244, 0, v244, s[84:85]
	v_add_f32_e32 v0, v243, v0
	v_cvt_pk_bf16_f32 v239, v242, v243
	s_waitcnt lgkmcnt(1)
	s_nop 0
	v_mfma_f32_32x32x16_bf16 v[64:79], v[6:9], v[236:239], v[64:79]
	ds_read_b128 v[2:5], v252 offset:49152
	v_exp_f32_e32 v246, v246
	v_cndmask_b32_e64 v245, 0, v245, s[86:87]
	v_add_f32_e32 v0, v244, v0
	v_exp_f32_e32 v247, v247
	s_waitcnt lgkmcnt(1)
	v_mfma_f32_32x32x16_bf16 v[48:63], v[10:13], v[236:239], v[48:63]
	ds_read_b128 v[6:9], v252 offset:57344
	v_cndmask_b32_e64 v246, 0, v246, s[88:89]
	v_add_f32_e32 v0, v245, v0
	v_cvt_pk_bf16_f32 v240, v244, v245
	v_exp_f32_e32 v248, v248
	s_waitcnt lgkmcnt(1)
	v_mfma_f32_32x32x16_bf16 v[32:47], v[2:5], v[236:239], v[32:47]
	v_xor_b32_e32 v253, 0xe0, v15
	ds_read_b128 v[10:13], v253 offset:32768
	v_cndmask_b32_e64 v247, 0, v247, s[90:91]
	v_add_f32_e32 v0, v246, v0
	v_exp_f32_e32 v249, v249
	v_cndmask_b32_e64 v248, 0, v248, s[92:93]
	s_waitcnt lgkmcnt(1)
	v_mfma_f32_32x32x16_bf16 v[16:31], v[6:9], v[236:239], v[16:31]
	ds_read_b128 v[2:5], v253 offset:40960
	v_add_f32_e32 v0, v247, v0
	v_cvt_pk_bf16_f32 v241, v246, v247
	v_exp_f32_e32 v250, v250
	v_cndmask_b32_e64 v249, 0, v249, s[94:95]
	v_add_f32_e32 v0, v248, v0
	v_exp_f32_e32 v251, v251
	v_cndmask_b32_e64 v250, 0, v250, s[96:97]
	v_add_f32_e32 v0, v249, v0
	v_cvt_pk_bf16_f32 v242, v248, v249
	v_cndmask_b32_e64 v251, 0, v251, vcc
	v_add_f32_e32 v0, v250, v0
	v_add_f32_e32 v0, v251, v0
	v_cvt_pk_bf16_f32 v243, v250, v251
	s_waitcnt lgkmcnt(1)
	s_nop 0
	v_mfma_f32_32x32x16_bf16 v[64:79], v[10:13], v[240:243], v[64:79]
	ds_read_b128 v[6:9], v253 offset:49152
	v_add_f32_e32 v196, v196, v0
	s_waitcnt lgkmcnt(1)
	v_mfma_f32_32x32x16_bf16 v[48:63], v[2:5], v[240:243], v[48:63]
	ds_read_b128 v[10:13], v253 offset:57344
	s_waitcnt lgkmcnt(1)
	v_mfma_f32_32x32x16_bf16 v[32:47], v[6:9], v[240:243], v[32:47]
	s_waitcnt lgkmcnt(0)
	v_mfma_f32_32x32x16_bf16 v[16:31], v[10:13], v[240:243], v[16:31]
	s_branch .LBB0_420
.Ldiff_fast0:
	s_lshl_b32 s1, s0, 16
	v_add3_u32 v14, s1, v215, v216
	v_add3_u32 v15, s1, v195, v224
	ds_read_b128 v[2:5], v14
	v_xor_b32_e32 v217, 32, v14
	ds_read_b128 v[6:9], v217
	v_xor_b32_e32 v222, 64, v14
	ds_read_b128 v[10:13], v222
	v_xor_b32_e32 v223, 0x60, v14
	ds_read_b128 v[218:221], v223
	s_waitcnt lgkmcnt(3)
	v_mfma_f32_32x32x16_bf16 v[144:159], v[2:5], v[160:163], 0
	v_xor_b32_e32 v225, 0x80, v14
	ds_read_b128 v[226:229], v225
	s_waitcnt lgkmcnt(3)
	v_mfma_f32_32x32x16_bf16 v[144:159], v[6:9], v[164:167], v[144:159]
	v_xor_b32_e32 v230, 0xa0, v14
	ds_read_b128 v[2:5], v230
	s_waitcnt lgkmcnt(3)
	v_mfma_f32_32x32x16_bf16 v[144:159], v[10:13], v[168:171], v[144:159]
	v_xor_b32_e32 v231, 0xc0, v14
	ds_read_b128 v[6:9], v231
	s_waitcnt lgkmcnt(3)
	v_mfma_f32_32x32x16_bf16 v[144:159], v[218:221], v[172:175], v[144:159]
	v_xor_b32_e32 v235, 0xe0, v14
	ds_read_b128 v[10:13], v235
	s_waitcnt lgkmcnt(3)
	v_mfma_f32_32x32x16_bf16 v[236:251], v[226:229], v[176:179], 0
	ds_read_b128 v[218:221], v15 offset:32768
	s_waitcnt lgkmcnt(3)
	v_mfma_f32_32x32x16_bf16 v[236:251], v[2:5], v[180:183], v[236:251]
	ds_read_b128 v[226:229], v15 offset:40960
	s_nop 3
	v_exp_f32_e32 v144, v144
	v_exp_f32_e32 v145, v145
	v_exp_f32_e32 v146, v146
	v_add_f32_e32 v0, v144, v145
	v_cvt_pk_bf16_f32 v144, v144, v145
	v_exp_f32_e32 v147, v147
	v_add_f32_e32 v0, v146, v0
	v_exp_f32_e32 v148, v148
	s_waitcnt lgkmcnt(3)
	v_mfma_f32_32x32x16_bf16 v[236:251], v[6:9], v[184:187], v[236:251]
	ds_read_b128 v[2:5], v15 offset:49152
	v_add_f32_e32 v0, v147, v0
	v_cvt_pk_bf16_f32 v145, v146, v147
	v_exp_f32_e32 v149, v149
	v_add_f32_e32 v0, v148, v0
	s_waitcnt lgkmcnt(3)
	v_mfma_f32_32x32x16_bf16 v[236:251], v[10:13], v[188:191], v[236:251]
	ds_read_b128 v[6:9], v15 offset:57344
	v_exp_f32_e32 v150, v150
	v_add_f32_e32 v0, v149, v0
	v_cvt_pk_bf16_f32 v146, v148, v149
	v_exp_f32_e32 v151, v151
	v_add_f32_e32 v0, v150, v0
	v_exp_f32_e32 v152, v152
	v_add_f32_e32 v0, v151, v0
	v_cvt_pk_bf16_f32 v147, v150, v151
	s_waitcnt lgkmcnt(3)
	s_nop 0
	v_mfma_f32_32x32x16_bf16 v[128:143], v[218:221], v[144:147], v[128:143]
	v_xor_b32_e32 v252, 32, v15
	ds_read_b128 v[10:13], v252 offset:32768
	v_exp_f32_e32 v153, v153
	v_add_f32_e32 v0, v152, v0
	v_exp_f32_e32 v154, v154
	v_add_f32_e32 v0, v153, v0
	s_waitcnt lgkmcnt(3)
	v_mfma_f32_32x32x16_bf16 v[112:127], v[226:229], v[144:147], v[112:127]
	ds_read_b128 v[218:221], v252 offset:40960
	v_cvt_pk_bf16_f32 v148, v152, v153
	v_exp_f32_e32 v155, v155
	v_add_f32_e32 v0, v154, v0
	v_exp_f32_e32 v156, v156
	s_waitcnt lgkmcnt(3)
	v_mfma_f32_32x32x16_bf16 v[96:111], v[2:5], v[144:147], v[96:111]
	ds_read_b128 v[226:229], v252 offset:49152
	v_add_f32_e32 v0, v155, v0
	v_cvt_pk_bf16_f32 v149, v154, v155
	v_exp_f32_e32 v157, v157
	v_add_f32_e32 v0, v156, v0
	s_waitcnt lgkmcnt(3)
	v_mfma_f32_32x32x16_bf16 v[80:95], v[6:9], v[144:147], v[80:95]
	ds_read_b128 v[2:5], v252 offset:57344
	v_exp_f32_e32 v158, v158
	v_add_f32_e32 v0, v157, v0
	v_cvt_pk_bf16_f32 v150, v156, v157
	v_exp_f32_e32 v159, v159
	v_add_f32_e32 v0, v158, v0
	v_add_f32_e32 v0, v159, v0
	v_cvt_pk_bf16_f32 v151, v158, v159
	s_waitcnt lgkmcnt(3)
	s_nop 0
	v_mfma_f32_32x32x16_bf16 v[128:143], v[10:13], v[148:151], v[128:143]
	ds_read_b128 v[6:9], v14 offset:8192
	v_add_f32_e32 v197, v197, v0
	v_exp_f32_e32 v236, v236
	v_exp_f32_e32 v237, v237
	v_exp_f32_e32 v238, v238
	s_waitcnt lgkmcnt(3)
	v_mfma_f32_32x32x16_bf16 v[112:127], v[218:221], v[148:151], v[112:127]
	ds_read_b128 v[10:13], v217 offset:8192
	v_add_f32_e32 v0, v236, v237
	v_cvt_pk_bf16_f32 v236, v236, v237
	v_exp_f32_e32 v239, v239
	v_add_f32_e32 v0, v238, v0
	s_waitcnt lgkmcnt(3)
	v_mfma_f32_32x32x16_bf16 v[96:111], v[226:229], v[148:151], v[96:111]
	ds_read_b128 v[218:221], v222 offset:8192
	v_exp_f32_e32 v240, v240
	v_add_f32_e32 v0, v239, v0
	v_cvt_pk_bf16_f32 v237, v238, v239
	v_exp_f32_e32 v241, v241
	s_waitcnt lgkmcnt(3)
	v_mfma_f32_32x32x16_bf16 v[80:95], v[2:5], v[148:151], v[80:95]
	ds_read_b128 v[226:229], v223 offset:8192
	v_add_f32_e32 v0, v240, v0
	v_exp_f32_e32 v242, v242
	v_add_f32_e32 v0, v241, v0
	v_cvt_pk_bf16_f32 v238, v240, v241
	s_waitcnt lgkmcnt(3)
	v_mfma_f32_32x32x16_bf16 v[144:159], v[6:9], v[160:163], 0
	ds_read_b128 v[2:5], v15 offset:32768
	v_exp_f32_e32 v243, v243
	v_add_f32_e32 v0, v242, v0
	v_exp_f32_e32 v244, v244
	v_add_f32_e32 v0, v243, v0
	s_waitcnt lgkmcnt(3)
	v_mfma_f32_32x32x16_bf16 v[144:159], v[10:13], v[164:167], v[144:159]
	ds_read_b128 v[6:9], v15 offset:40960
	v_cvt_pk_bf16_f32 v239, v242, v243
	v_exp_f32_e32 v245, v245
	v_add_f32_e32 v0, v244, v0
	v_exp_f32_e32 v246, v246
	s_waitcnt lgkmcnt(3)
	v_mfma_f32_32x32x16_bf16 v[144:159], v[218:221], v[168:171], v[144:159]
	ds_read_b128 v[10:13], v15 offset:49152
	v_add_f32_e32 v0, v245, v0
	v_cvt_pk_bf16_f32 v240, v244, v245
	v_exp_f32_e32 v247, v247
	v_add_f32_e32 v0, v246, v0
	s_waitcnt lgkmcnt(3)
	v_mfma_f32_32x32x16_bf16 v[144:159], v[226:229], v[172:175], v[144:159]
	ds_read_b128 v[218:221], v15 offset:57344
	v_exp_f32_e32 v248, v248
	v_add_f32_e32 v0, v247, v0
	v_cvt_pk_bf16_f32 v241, v246, v247
	v_exp_f32_e32 v249, v249
	s_waitcnt lgkmcnt(3)
	v_mfma_f32_32x32x16_bf16 v[64:79], v[2:5], v[236:239], v[64:79]
	v_xor_b32_e32 v253, 32, v15
	ds_read_b128 v[226:229], v253 offset:32768
	v_add_f32_e32 v0, v248, v0
	v_exp_f32_e32 v250, v250
	v_add_f32_e32 v0, v249, v0
	v_cvt_pk_bf16_f32 v242, v248, v249
	s_waitcnt lgkmcnt(3)
	v_mfma_f32_32x32x16_bf16 v[48:63], v[6:9], v[236:239], v[48:63]
	ds_read_b128 v[2:5], v253 offset:40960
	v_exp_f32_e32 v251, v251
	v_add_f32_e32 v0, v250, v0
	v_add_f32_e32 v0, v251, v0
	v_cvt_pk_bf16_f32 v243, v250, v251
	s_waitcnt lgkmcnt(3)
	v_mfma_f32_32x32x16_bf16 v[32:47], v[10:13], v[236:239], v[32:47]
	ds_read_b128 v[6:9], v253 offset:49152
	v_add_f32_e32 v196, v196, v0
	v_exp_f32_e32 v144, v144
	v_exp_f32_e32 v145, v145
	v_exp_f32_e32 v146, v146
	s_waitcnt lgkmcnt(3)
	v_mfma_f32_32x32x16_bf16 v[16:31], v[218:221], v[236:239], v[16:31]
	ds_read_b128 v[10:13], v253 offset:57344
	v_add_f32_e32 v0, v144, v145
	v_cvt_pk_bf16_f32 v144, v144, v145
	v_exp_f32_e32 v147, v147
	v_add_f32_e32 v0, v146, v0
	s_waitcnt lgkmcnt(3)
	v_mfma_f32_32x32x16_bf16 v[64:79], v[226:229], v[240:243], v[64:79]
	ds_read_b128 v[218:221], v225 offset:8192
	v_exp_f32_e32 v148, v148
	v_add_f32_e32 v0, v147, v0
	v_cvt_pk_bf16_f32 v145, v146, v147
	v_exp_f32_e32 v149, v149
	s_waitcnt lgkmcnt(3)
	v_mfma_f32_32x32x16_bf16 v[48:63], v[2:5], v[240:243], v[48:63]
	ds_read_b128 v[226:229], v230 offset:8192
	v_add_f32_e32 v0, v148, v0
	v_exp_f32_e32 v150, v150
	v_add_f32_e32 v0, v149, v0
	v_cvt_pk_bf16_f32 v146, v148, v149
	s_waitcnt lgkmcnt(3)
	v_mfma_f32_32x32x16_bf16 v[32:47], v[6:9], v[240:243], v[32:47]
	ds_read_b128 v[2:5], v231 offset:8192
	v_exp_f32_e32 v151, v151
	v_add_f32_e32 v0, v150, v0
	v_exp_f32_e32 v152, v152
	v_add_f32_e32 v0, v151, v0
	s_waitcnt lgkmcnt(3)
	v_mfma_f32_32x32x16_bf16 v[16:31], v[10:13], v[240:243], v[16:31]
	ds_read_b128 v[6:9], v235 offset:8192
	v_cvt_pk_bf16_f32 v147, v150, v151
	v_exp_f32_e32 v153, v153
	v_add_f32_e32 v0, v152, v0
	v_exp_f32_e32 v154, v154
	s_waitcnt lgkmcnt(3)
	v_mfma_f32_32x32x16_bf16 v[236:251], v[218:221], v[176:179], 0
	v_xor_b32_e32 v252, 64, v15
	ds_read_b128 v[10:13], v252 offset:32768
	v_add_f32_e32 v0, v153, v0
	v_cvt_pk_bf16_f32 v148, v152, v153
	v_exp_f32_e32 v155, v155
	v_add_f32_e32 v0, v154, v0
	s_waitcnt lgkmcnt(3)
	v_mfma_f32_32x32x16_bf16 v[236:251], v[226:229], v[180:183], v[236:251]
	ds_read_b128 v[218:221], v252 offset:40960
	v_exp_f32_e32 v156, v156
	v_add_f32_e32 v0, v155, v0
	v_cvt_pk_bf16_f32 v149, v154, v155
	v_exp_f32_e32 v157, v157
	s_waitcnt lgkmcnt(3)
	v_mfma_f32_32x32x16_bf16 v[236:251], v[2:5], v[184:187], v[236:251]
	ds_read_b128 v[226:229], v252 offset:49152
	v_add_f32_e32 v0, v156, v0
	v_exp_f32_e32 v158, v158
	v_add_f32_e32 v0, v157, v0
	v_cvt_pk_bf16_f32 v150, v156, v157
	s_waitcnt lgkmcnt(3)
	v_mfma_f32_32x32x16_bf16 v[236:251], v[6:9], v[188:191], v[236:251]
	ds_read_b128 v[2:5], v252 offset:57344
	v_exp_f32_e32 v159, v159
	v_add_f32_e32 v0, v158, v0
	v_add_f32_e32 v0, v159, v0
	v_cvt_pk_bf16_f32 v151, v158, v159
	s_waitcnt lgkmcnt(3)
	v_mfma_f32_32x32x16_bf16 v[128:143], v[10:13], v[144:147], v[128:143]
	v_xor_b32_e32 v253, 0x60, v15
	ds_read_b128 v[6:9], v253 offset:32768
	v_add_f32_e32 v197, v197, v0
	s_waitcnt lgkmcnt(3)
	v_mfma_f32_32x32x16_bf16 v[112:127], v[218:221], v[144:147], v[112:127]
	ds_read_b128 v[10:13], v253 offset:40960
	v_exp_f32_e32 v236, v236
	v_exp_f32_e32 v237, v237
	v_exp_f32_e32 v238, v238
	v_add_f32_e32 v0, v236, v237
	v_cvt_pk_bf16_f32 v236, v236, v237
	v_exp_f32_e32 v239, v239
	v_add_f32_e32 v0, v238, v0
	s_waitcnt lgkmcnt(3)
	v_mfma_f32_32x32x16_bf16 v[96:111], v[226:229], v[144:147], v[96:111]
	ds_read_b128 v[218:221], v253 offset:49152
	v_exp_f32_e32 v240, v240
	v_add_f32_e32 v0, v239, v0
	v_cvt_pk_bf16_f32 v237, v238, v239
	v_exp_f32_e32 v241, v241
	s_waitcnt lgkmcnt(3)
	v_mfma_f32_32x32x16_bf16 v[80:95], v[2:5], v[144:147], v[80:95]
	ds_read_b128 v[226:229], v253 offset:57344
	v_add_f32_e32 v0, v240, v0
	v_exp_f32_e32 v242, v242
	v_add_f32_e32 v0, v241, v0
	v_cvt_pk_bf16_f32 v238, v240, v241
	s_waitcnt lgkmcnt(3)
	v_mfma_f32_32x32x16_bf16 v[128:143], v[6:9], v[148:151], v[128:143]
	ds_read_b128 v[2:5], v14 offset:16384
	v_exp_f32_e32 v243, v243
	v_add_f32_e32 v0, v242, v0
	v_exp_f32_e32 v244, v244
	v_add_f32_e32 v0, v243, v0
	s_waitcnt lgkmcnt(3)
	v_mfma_f32_32x32x16_bf16 v[112:127], v[10:13], v[148:151], v[112:127]
	ds_read_b128 v[6:9], v217 offset:16384
	v_cvt_pk_bf16_f32 v239, v242, v243
	v_exp_f32_e32 v245, v245
	v_add_f32_e32 v0, v244, v0
	v_exp_f32_e32 v246, v246
	s_waitcnt lgkmcnt(3)
	v_mfma_f32_32x32x16_bf16 v[96:111], v[218:221], v[148:151], v[96:111]
	ds_read_b128 v[10:13], v222 offset:16384
	v_add_f32_e32 v0, v245, v0
	v_cvt_pk_bf16_f32 v240, v244, v245
	v_exp_f32_e32 v247, v247
	v_add_f32_e32 v0, v246, v0
	s_waitcnt lgkmcnt(3)
	v_mfma_f32_32x32x16_bf16 v[80:95], v[226:229], v[148:151], v[80:95]
	ds_read_b128 v[218:221], v223 offset:16384
	v_exp_f32_e32 v248, v248
	v_add_f32_e32 v0, v247, v0
	v_cvt_pk_bf16_f32 v241, v246, v247
	v_exp_f32_e32 v249, v249
	s_waitcnt lgkmcnt(3)
	v_mfma_f32_32x32x16_bf16 v[144:159], v[2:5], v[160:163], 0
	v_xor_b32_e32 v252, 64, v15
	ds_read_b128 v[226:229], v252 offset:32768
	v_add_f32_e32 v0, v248, v0
	v_exp_f32_e32 v250, v250
	v_add_f32_e32 v0, v249, v0
	v_cvt_pk_bf16_f32 v242, v248, v249
	s_waitcnt lgkmcnt(3)
	v_mfma_f32_32x32x16_bf16 v[144:159], v[6:9], v[164:167], v[144:159]
	ds_read_b128 v[2:5], v252 offset:40960
	v_exp_f32_e32 v251, v251
	v_add_f32_e32 v0, v250, v0
	v_add_f32_e32 v0, v251, v0
	v_cvt_pk_bf16_f32 v243, v250, v251
	s_waitcnt lgkmcnt(3)
	v_mfma_f32_32x32x16_bf16 v[144:159], v[10:13], v[168:171], v[144:159]
	ds_read_b128 v[6:9], v252 offset:49152
	v_add_f32_e32 v196, v196, v0
	s_waitcnt lgkmcnt(3)
	v_mfma_f32_32x32x16_bf16 v[144:159], v[218:221], v[172:175], v[144:159]
	ds_read_b128 v[10:13], v252 offset:57344
	s_waitcnt lgkmcnt(3)
	v_mfma_f32_32x32x16_bf16 v[64:79], v[226:229], v[236:239], v[64:79]
	v_xor_b32_e32 v253, 0x60, v15
	ds_read_b128 v[218:221], v253 offset:32768
	s_waitcnt lgkmcnt(3)
	v_mfma_f32_32x32x16_bf16 v[48:63], v[2:5], v[236:239], v[48:63]
	ds_read_b128 v[226:229], v253 offset:40960
	s_nop 3
	v_exp_f32_e32 v144, v144
	v_exp_f32_e32 v145, v145
	v_exp_f32_e32 v146, v146
	v_add_f32_e32 v0, v144, v145
	v_cvt_pk_bf16_f32 v144, v144, v145
	v_exp_f32_e32 v147, v147
	v_add_f32_e32 v0, v146, v0
	v_exp_f32_e32 v148, v148
	s_waitcnt lgkmcnt(3)
	v_mfma_f32_32x32x16_bf16 v[32:47], v[6:9], v[236:239], v[32:47]
	ds_read_b128 v[2:5], v253 offset:49152
	v_add_f32_e32 v0, v147, v0
	v_cvt_pk_bf16_f32 v145, v146, v147
	v_exp_f32_e32 v149, v149
	v_add_f32_e32 v0, v148, v0
	s_waitcnt lgkmcnt(3)
	v_mfma_f32_32x32x16_bf16 v[16:31], v[10:13], v[236:239], v[16:31]
	ds_read_b128 v[6:9], v253 offset:57344
	v_exp_f32_e32 v150, v150
	v_add_f32_e32 v0, v149, v0
	v_cvt_pk_bf16_f32 v146, v148, v149
	v_exp_f32_e32 v151, v151
	s_waitcnt lgkmcnt(3)
	v_mfma_f32_32x32x16_bf16 v[64:79], v[218:221], v[240:243], v[64:79]
	ds_read_b128 v[10:13], v225 offset:16384
	v_add_f32_e32 v0, v150, v0
	v_exp_f32_e32 v152, v152
	v_add_f32_e32 v0, v151, v0
	v_cvt_pk_bf16_f32 v147, v150, v151
	s_waitcnt lgkmcnt(3)
	v_mfma_f32_32x32x16_bf16 v[48:63], v[226:229], v[240:243], v[48:63]
	ds_read_b128 v[218:221], v230 offset:16384
	v_exp_f32_e32 v153, v153
	v_add_f32_e32 v0, v152, v0
	v_exp_f32_e32 v154, v154
	v_add_f32_e32 v0, v153, v0
	s_waitcnt lgkmcnt(3)
	v_mfma_f32_32x32x16_bf16 v[32:47], v[2:5], v[240:243], v[32:47]
	ds_read_b128 v[226:229], v231 offset:16384
	v_cvt_pk_bf16_f32 v148, v152, v153
	v_exp_f32_e32 v155, v155
	v_add_f32_e32 v0, v154, v0
	v_exp_f32_e32 v156, v156
	s_waitcnt lgkmcnt(3)
	v_mfma_f32_32x32x16_bf16 v[16:31], v[6:9], v[240:243], v[16:31]
	ds_read_b128 v[2:5], v235 offset:16384
	v_add_f32_e32 v0, v155, v0
	v_cvt_pk_bf16_f32 v149, v154, v155
	v_exp_f32_e32 v157, v157
	v_add_f32_e32 v0, v156, v0
	s_waitcnt lgkmcnt(3)
	v_mfma_f32_32x32x16_bf16 v[236:251], v[10:13], v[176:179], 0
	v_xor_b32_e32 v252, 0x80, v15
	ds_read_b128 v[6:9], v252 offset:32768
	v_exp_f32_e32 v158, v158
	v_add_f32_e32 v0, v157, v0
	v_cvt_pk_bf16_f32 v150, v156, v157
	v_exp_f32_e32 v159, v159
	s_waitcnt lgkmcnt(3)
	v_mfma_f32_32x32x16_bf16 v[236:251], v[218:221], v[180:183], v[236:251]
	ds_read_b128 v[10:13], v252 offset:40960
	v_add_f32_e32 v0, v158, v0
	v_add_f32_e32 v0, v159, v0
	v_cvt_pk_bf16_f32 v151, v158, v159
	v_add_f32_e32 v197, v197, v0
	s_waitcnt lgkmcnt(3)
	v_mfma_f32_32x32x16_bf16 v[236:251], v[226:229], v[184:187], v[236:251]
	ds_read_b128 v[218:221], v252 offset:49152
	s_waitcnt lgkmcnt(3)
	v_mfma_f32_32x32x16_bf16 v[236:251], v[2:5], v[188:191], v[236:251]
	ds_read_b128 v[226:229], v252 offset:57344
	s_waitcnt lgkmcnt(3)
	v_mfma_f32_32x32x16_bf16 v[128:143], v[6:9], v[144:147], v[128:143]
	v_xor_b32_e32 v253, 0xa0, v15
	ds_read_b128 v[2:5], v253 offset:32768
	s_waitcnt lgkmcnt(3)
	v_mfma_f32_32x32x16_bf16 v[112:127], v[10:13], v[144:147], v[112:127]
	ds_read_b128 v[6:9], v253 offset:40960
	s_nop 3
	v_exp_f32_e32 v236, v236
	v_exp_f32_e32 v237, v237
	v_exp_f32_e32 v238, v238
	v_add_f32_e32 v0, v236, v237
	v_cvt_pk_bf16_f32 v236, v236, v237
	v_exp_f32_e32 v239, v239
	v_add_f32_e32 v0, v238, v0
	v_exp_f32_e32 v240, v240
	s_waitcnt lgkmcnt(3)
	v_mfma_f32_32x32x16_bf16 v[96:111], v[218:221], v[144:147], v[96:111]
	ds_read_b128 v[10:13], v253 offset:49152
	v_add_f32_e32 v0, v239, v0
	v_cvt_pk_bf16_f32 v237, v238, v239
	v_exp_f32_e32 v241, v241
	v_add_f32_e32 v0, v240, v0
	s_waitcnt lgkmcnt(3)
	v_mfma_f32_32x32x16_bf16 v[80:95], v[226:229], v[144:147], v[80:95]
	ds_read_b128 v[218:221], v253 offset:57344
	v_exp_f32_e32 v242, v242
	v_add_f32_e32 v0, v241, v0
	v_cvt_pk_bf16_f32 v238, v240, v241
	v_exp_f32_e32 v243, v243
	s_waitcnt lgkmcnt(3)
	v_mfma_f32_32x32x16_bf16 v[128:143], v[2:5], v[148:151], v[128:143]
	ds_read_b128 v[226:229], v14 offset:24576
	v_add_f32_e32 v0, v242, v0
	v_exp_f32_e32 v244, v244
	v_add_f32_e32 v0, v243, v0
	v_cvt_pk_bf16_f32 v239, v242, v243
	s_waitcnt lgkmcnt(3)
	v_mfma_f32_32x32x16_bf16 v[112:127], v[6:9], v[148:151], v[112:127]
	ds_read_b128 v[2:5], v217 offset:24576
	v_exp_f32_e32 v245, v245
	v_add_f32_e32 v0, v244, v0
	v_exp_f32_e32 v246, v246
	v_add_f32_e32 v0, v245, v0
	s_waitcnt lgkmcnt(3)
	v_mfma_f32_32x32x16_bf16 v[96:111], v[10:13], v[148:151], v[96:111]
	ds_read_b128 v[6:9], v222 offset:24576
	v_cvt_pk_bf16_f32 v240, v244, v245
	v_exp_f32_e32 v247, v247
	v_add_f32_e32 v0, v246, v0
	v_exp_f32_e32 v248, v248
	s_waitcnt lgkmcnt(3)
	v_mfma_f32_32x32x16_bf16 v[80:95], v[218:221], v[148:151], v[80:95]
	ds_read_b128 v[10:13], v223 offset:24576
	v_add_f32_e32 v0, v247, v0
	v_cvt_pk_bf16_f32 v241, v246, v247
	v_exp_f32_e32 v249, v249
	v_add_f32_e32 v0, v248, v0
	s_waitcnt lgkmcnt(3)
	v_mfma_f32_32x32x16_bf16 v[144:159], v[226:229], v[160:163], 0
	v_xor_b32_e32 v252, 0x80, v15
	ds_read_b128 v[218:221], v252 offset:32768
	v_exp_f32_e32 v250, v250
	v_add_f32_e32 v0, v249, v0
	v_cvt_pk_bf16_f32 v242, v248, v249
	v_exp_f32_e32 v251, v251
	s_waitcnt lgkmcnt(3)
	v_mfma_f32_32x32x16_bf16 v[144:159], v[2:5], v[164:167], v[144:159]
	ds_read_b128 v[226:229], v252 offset:40960
	v_add_f32_e32 v0, v250, v0
	v_add_f32_e32 v0, v251, v0
	v_cvt_pk_bf16_f32 v243, v250, v251
	v_add_f32_e32 v196, v196, v0
	s_waitcnt lgkmcnt(3)
	v_mfma_f32_32x32x16_bf16 v[144:159], v[6:9], v[168:171], v[144:159]
	ds_read_b128 v[2:5], v252 offset:49152
	s_waitcnt lgkmcnt(3)
	v_mfma_f32_32x32x16_bf16 v[144:159], v[10:13], v[172:175], v[144:159]
	ds_read_b128 v[6:9], v252 offset:57344
	s_waitcnt lgkmcnt(3)
	v_mfma_f32_32x32x16_bf16 v[64:79], v[218:221], v[236:239], v[64:79]
	v_xor_b32_e32 v253, 0xa0, v15
	ds_read_b128 v[10:13], v253 offset:32768
	s_waitcnt lgkmcnt(3)
	v_mfma_f32_32x32x16_bf16 v[48:63], v[226:229], v[236:239], v[48:63]
	ds_read_b128 v[218:221], v253 offset:40960
	s_nop 3
	v_exp_f32_e32 v144, v144
	v_exp_f32_e32 v145, v145
	v_exp_f32_e32 v146, v146
	v_add_f32_e32 v0, v144, v145
	v_cvt_pk_bf16_f32 v144, v144, v145
	v_exp_f32_e32 v147, v147
	v_add_f32_e32 v0, v146, v0
	v_exp_f32_e32 v148, v148
	s_waitcnt lgkmcnt(3)
	v_mfma_f32_32x32x16_bf16 v[32:47], v[2:5], v[236:239], v[32:47]
	ds_read_b128 v[226:229], v253 offset:49152
	v_add_f32_e32 v0, v147, v0
	v_cvt_pk_bf16_f32 v145, v146, v147
	v_exp_f32_e32 v149, v149
	v_add_f32_e32 v0, v148, v0
	s_waitcnt lgkmcnt(3)
	v_mfma_f32_32x32x16_bf16 v[16:31], v[6:9], v[236:239], v[16:31]
	ds_read_b128 v[2:5], v253 offset:57344
	v_exp_f32_e32 v150, v150
	v_add_f32_e32 v0, v149, v0
	v_cvt_pk_bf16_f32 v146, v148, v149
	v_exp_f32_e32 v151, v151
	s_waitcnt lgkmcnt(3)
	v_mfma_f32_32x32x16_bf16 v[64:79], v[10:13], v[240:243], v[64:79]
	ds_read_b128 v[6:9], v225 offset:24576
	v_add_f32_e32 v0, v150, v0
	v_exp_f32_e32 v152, v152
	v_add_f32_e32 v0, v151, v0
	v_cvt_pk_bf16_f32 v147, v150, v151
	s_waitcnt lgkmcnt(3)
	v_mfma_f32_32x32x16_bf16 v[48:63], v[218:221], v[240:243], v[48:63]
	ds_read_b128 v[10:13], v230 offset:24576
	v_exp_f32_e32 v153, v153
	v_add_f32_e32 v0, v152, v0
	v_exp_f32_e32 v154, v154
	v_add_f32_e32 v0, v153, v0
	s_waitcnt lgkmcnt(3)
	v_mfma_f32_32x32x16_bf16 v[32:47], v[226:229], v[240:243], v[32:47]
	ds_read_b128 v[218:221], v231 offset:24576
	v_cvt_pk_bf16_f32 v148, v152, v153
	v_exp_f32_e32 v155, v155
	v_add_f32_e32 v0, v154, v0
	v_exp_f32_e32 v156, v156
	s_waitcnt lgkmcnt(3)
	v_mfma_f32_32x32x16_bf16 v[16:31], v[2:5], v[240:243], v[16:31]
	ds_read_b128 v[226:229], v235 offset:24576
	v_add_f32_e32 v0, v155, v0
	v_cvt_pk_bf16_f32 v149, v154, v155
	v_exp_f32_e32 v157, v157
	v_add_f32_e32 v0, v156, v0
	s_waitcnt lgkmcnt(3)
	v_mfma_f32_32x32x16_bf16 v[236:251], v[6:9], v[176:179], 0
	v_xor_b32_e32 v252, 0xc0, v15
	ds_read_b128 v[2:5], v252 offset:32768
	v_exp_f32_e32 v158, v158
	v_add_f32_e32 v0, v157, v0
	v_cvt_pk_bf16_f32 v150, v156, v157
	v_exp_f32_e32 v159, v159
	s_waitcnt lgkmcnt(3)
	v_mfma_f32_32x32x16_bf16 v[236:251], v[10:13], v[180:183], v[236:251]
	ds_read_b128 v[6:9], v252 offset:40960
	v_add_f32_e32 v0, v158, v0
	v_add_f32_e32 v0, v159, v0
	v_cvt_pk_bf16_f32 v151, v158, v159
	v_add_f32_e32 v197, v197, v0
	s_waitcnt lgkmcnt(3)
	v_mfma_f32_32x32x16_bf16 v[236:251], v[218:221], v[184:187], v[236:251]
	ds_read_b128 v[10:13], v252 offset:49152
	s_waitcnt lgkmcnt(3)
	v_mfma_f32_32x32x16_bf16 v[236:251], v[226:229], v[188:191], v[236:251]
	ds_read_b128 v[218:221], v252 offset:57344
	s_waitcnt lgkmcnt(3)
	v_mfma_f32_32x32x16_bf16 v[128:143], v[2:5], v[144:147], v[128:143]
	v_xor_b32_e32 v253, 0xe0, v15
	ds_read_b128 v[226:229], v253 offset:32768
	s_waitcnt lgkmcnt(3)
	v_mfma_f32_32x32x16_bf16 v[112:127], v[6:9], v[144:147], v[112:127]
	ds_read_b128 v[2:5], v253 offset:40960
	s_nop 3
	v_exp_f32_e32 v236, v236
	v_exp_f32_e32 v237, v237
	v_exp_f32_e32 v238, v238
	v_add_f32_e32 v0, v236, v237
	v_cvt_pk_bf16_f32 v236, v236, v237
	v_exp_f32_e32 v239, v239
	v_add_f32_e32 v0, v238, v0
	v_exp_f32_e32 v240, v240
	s_waitcnt lgkmcnt(3)
	v_mfma_f32_32x32x16_bf16 v[96:111], v[10:13], v[144:147], v[96:111]
	ds_read_b128 v[6:9], v253 offset:49152
	v_add_f32_e32 v0, v239, v0
	v_cvt_pk_bf16_f32 v237, v238, v239
	v_exp_f32_e32 v241, v241
	v_add_f32_e32 v0, v240, v0
	s_waitcnt lgkmcnt(3)
	v_mfma_f32_32x32x16_bf16 v[80:95], v[218:221], v[144:147], v[80:95]
	ds_read_b128 v[10:13], v253 offset:57344
	v_exp_f32_e32 v242, v242
	v_add_f32_e32 v0, v241, v0
	v_cvt_pk_bf16_f32 v238, v240, v241
	v_exp_f32_e32 v243, v243
	s_waitcnt lgkmcnt(3)
	v_mfma_f32_32x32x16_bf16 v[128:143], v[226:229], v[148:151], v[128:143]
	v_xor_b32_e32 v252, 0xc0, v15
	ds_read_b128 v[218:221], v252 offset:32768
	v_add_f32_e32 v0, v242, v0
	v_exp_f32_e32 v244, v244
	v_add_f32_e32 v0, v243, v0
	v_cvt_pk_bf16_f32 v239, v242, v243
	s_waitcnt lgkmcnt(3)
	v_mfma_f32_32x32x16_bf16 v[112:127], v[2:5], v[148:151], v[112:127]
	ds_read_b128 v[226:229], v252 offset:40960
	v_exp_f32_e32 v245, v245
	v_add_f32_e32 v0, v244, v0
	v_exp_f32_e32 v246, v246
	v_add_f32_e32 v0, v245, v0
	s_waitcnt lgkmcnt(3)
	v_mfma_f32_32x32x16_bf16 v[96:111], v[6:9], v[148:151], v[96:111]
	ds_read_b128 v[2:5], v252 offset:49152
	v_cvt_pk_bf16_f32 v240, v244, v245
	v_exp_f32_e32 v247, v247
	v_add_f32_e32 v0, v246, v0
	v_exp_f32_e32 v248, v248
	s_waitcnt lgkmcnt(3)
	v_mfma_f32_32x32x16_bf16 v[80:95], v[10:13], v[148:151], v[80:95]
	ds_read_b128 v[6:9], v252 offset:57344
	v_add_f32_e32 v0, v247, v0
	v_cvt_pk_bf16_f32 v241, v246, v247
	v_exp_f32_e32 v249, v249
	v_add_f32_e32 v0, v248, v0
	s_waitcnt lgkmcnt(3)
	v_mfma_f32_32x32x16_bf16 v[64:79], v[218:221], v[236:239], v[64:79]
	v_xor_b32_e32 v253, 0xe0, v15
	ds_read_b128 v[10:13], v253 offset:32768
	v_exp_f32_e32 v250, v250
	v_add_f32_e32 v0, v249, v0
	v_cvt_pk_bf16_f32 v242, v248, v249
	v_exp_f32_e32 v251, v251
	s_waitcnt lgkmcnt(3)
	v_mfma_f32_32x32x16_bf16 v[48:63], v[226:229], v[236:239], v[48:63]
	ds_read_b128 v[218:221], v253 offset:40960
	v_add_f32_e32 v0, v250, v0
	v_add_f32_e32 v0, v251, v0
	v_cvt_pk_bf16_f32 v243, v250, v251
	v_add_f32_e32 v196, v196, v0
	s_waitcnt lgkmcnt(3)
	v_mfma_f32_32x32x16_bf16 v[32:47], v[2:5], v[236:239], v[32:47]
	ds_read_b128 v[226:229], v253 offset:49152
	s_waitcnt lgkmcnt(3)
	v_mfma_f32_32x32x16_bf16 v[16:31], v[6:9], v[236:239], v[16:31]
	ds_read_b128 v[2:5], v253 offset:57344
	s_waitcnt lgkmcnt(3)
	v_mfma_f32_32x32x16_bf16 v[64:79], v[10:13], v[240:243], v[64:79]
	s_waitcnt lgkmcnt(2)
	v_mfma_f32_32x32x16_bf16 v[48:63], v[218:221], v[240:243], v[48:63]
	s_waitcnt lgkmcnt(1)
	v_mfma_f32_32x32x16_bf16 v[32:47], v[226:229], v[240:243], v[32:47]
	s_waitcnt lgkmcnt(0)
	v_mfma_f32_32x32x16_bf16 v[16:31], v[2:5], v[240:243], v[16:31]

.LBB0_423:
	s_add_i32 s1, s35, 0xffffff81
	s_cmp_gt_u32 s1, s34
	s_cbranch_scc1 .LBB0_420
	s_cmp_gt_u32 s35, s31
	s_cbranch_scc0 .Ldiff_fast0
	s_branch .Ldiff_mask0

.LBB0_438:
	s_or_b64 exec, exec, s[0:1]
	v_ashrrev_i32_e32 v193, 31, v192
	v_lshlrev_b64 v[2:3], 2, v[192:193]
	v_lshl_add_u64 v[4:5], s[62:63], 0, v[2:3]
	v_mov_b64_e32 v[6:7], v[4:5]
	s_barrier
	v_lshl_add_u64 v[2:3], s[64:65], 0, v[2:3]
	s_mov_b64 s[0:1], 0x1000
	v_lshl_add_u64 v[6:7], v[4:5], 0, s[0:1]
	s_mov_b64 s[0:1], 0x3000
	v_lshl_add_u64 v[8:9], v[4:5], 0, s[0:1]
	s_mov_b64 s[0:1], 0x5000
	v_lshl_add_u64 v[10:11], v[4:5], 0, s[0:1]
	s_mov_b64 s[0:1], 0x7000
	v_lshl_add_u64 v[12:13], v[4:5], 0, s[0:1]
	global_load_dword v160, v[6:7], off offset:-4096 nt
	global_load_dword v161, v[6:7], off offset:-3840 nt
	global_load_dword v162, v[6:7], off offset:-3584 nt
	global_load_dword v163, v[6:7], off offset:-3328 nt
	global_load_dword v164, v[6:7], off offset:-3072 nt
	global_load_dword v165, v[6:7], off offset:-2816 nt
	global_load_dword v166, v[6:7], off offset:-2560 nt
	global_load_dword v167, v[6:7], off offset:-2304 nt
	global_load_dword v168, v[6:7], off offset:-2048 nt
	global_load_dword v169, v[6:7], off offset:-1792 nt
	global_load_dword v170, v[6:7], off offset:-1536 nt
	global_load_dword v171, v[6:7], off offset:-1280 nt
	global_load_dword v172, v[6:7], off offset:-1024 nt
	global_load_dword v173, v[6:7], off offset:-768 nt
	global_load_dword v174, v[6:7], off offset:-512 nt
	global_load_dword v175, v[6:7], off offset:-256 nt
	global_load_dword v176, v[6:7], off nt
	global_load_dword v177, v[6:7], off offset:256 nt
	global_load_dword v178, v[6:7], off offset:512 nt
	global_load_dword v179, v[6:7], off offset:768 nt
	global_load_dword v180, v[6:7], off offset:1024 nt
	global_load_dword v181, v[6:7], off offset:1280 nt
	global_load_dword v182, v[6:7], off offset:1536 nt
	global_load_dword v183, v[6:7], off offset:1792 nt
	global_load_dword v184, v[6:7], off offset:2048 nt
	global_load_dword v185, v[6:7], off offset:2304 nt
	global_load_dword v186, v[6:7], off offset:2560 nt
	global_load_dword v187, v[6:7], off offset:2816 nt
	global_load_dword v188, v[6:7], off offset:3072 nt
	global_load_dword v189, v[6:7], off offset:3328 nt
	global_load_dword v190, v[6:7], off offset:3584 nt
	global_load_dword v191, v[6:7], off offset:3840 nt
	global_load_dword v198, v[8:9], off offset:-4096 nt
	global_load_dword v199, v[8:9], off offset:-3840 nt
	global_load_dword v200, v[8:9], off offset:-3584 nt
	global_load_dword v201, v[8:9], off offset:-3328 nt
	global_load_dword v202, v[8:9], off offset:-3072 nt
	global_load_dword v203, v[8:9], off offset:-2816 nt
	global_load_dword v204, v[8:9], off offset:-2560 nt
	global_load_dword v205, v[8:9], off offset:-2304 nt
	global_load_dword v206, v[8:9], off offset:-2048 nt
	global_load_dword v207, v[8:9], off offset:-1792 nt
	global_load_dword v208, v[8:9], off offset:-1536 nt
	global_load_dword v209, v[8:9], off offset:-1280 nt
	global_load_dword v210, v[8:9], off offset:-1024 nt
	global_load_dword v211, v[8:9], off offset:-768 nt
	global_load_dword v212, v[8:9], off offset:-512 nt
	global_load_dword v213, v[8:9], off offset:-256 nt
	s_waitcnt vmcnt(32)
	v_pk_add_f32 v[128:129], v[128:129], v[160:161]
	v_pk_add_f32 v[130:131], v[130:131], v[162:163]
	v_pk_add_f32 v[132:133], v[132:133], v[164:165]
	v_pk_add_f32 v[134:135], v[134:135], v[166:167]
	v_pk_add_f32 v[136:137], v[136:137], v[168:169]
	v_pk_add_f32 v[138:139], v[138:139], v[170:171]
	v_pk_add_f32 v[140:141], v[140:141], v[172:173]
	v_pk_add_f32 v[142:143], v[142:143], v[174:175]
	global_load_dword v160, v[8:9], off nt
	global_load_dword v161, v[8:9], off offset:256 nt
	global_load_dword v162, v[8:9], off offset:512 nt
	global_load_dword v163, v[8:9], off offset:768 nt
	global_load_dword v164, v[8:9], off offset:1024 nt
	global_load_dword v165, v[8:9], off offset:1280 nt
	global_load_dword v166, v[8:9], off offset:1536 nt
	global_load_dword v167, v[8:9], off offset:1792 nt
	global_load_dword v168, v[8:9], off offset:2048 nt
	global_load_dword v169, v[8:9], off offset:2304 nt
	global_load_dword v170, v[8:9], off offset:2560 nt
	global_load_dword v171, v[8:9], off offset:2816 nt
	global_load_dword v172, v[8:9], off offset:3072 nt
	global_load_dword v173, v[8:9], off offset:3328 nt
	global_load_dword v174, v[8:9], off offset:3584 nt
	global_load_dword v175, v[8:9], off offset:3840 nt
	s_waitcnt vmcnt(32)
	v_pk_add_f32 v[112:113], v[112:113], v[176:177]
	v_pk_add_f32 v[114:115], v[114:115], v[178:179]
	v_pk_add_f32 v[116:117], v[116:117], v[180:181]
	v_pk_add_f32 v[118:119], v[118:119], v[182:183]
	v_pk_add_f32 v[120:121], v[120:121], v[184:185]
	v_pk_add_f32 v[122:123], v[122:123], v[186:187]
	v_pk_add_f32 v[124:125], v[124:125], v[188:189]
	v_pk_add_f32 v[126:127], v[126:127], v[190:191]
	global_load_dword v176, v[10:11], off offset:-4096 nt
	global_load_dword v177, v[10:11], off offset:-3840 nt
	global_load_dword v178, v[10:11], off offset:-3584 nt
	global_load_dword v179, v[10:11], off offset:-3328 nt
	global_load_dword v180, v[10:11], off offset:-3072 nt
	global_load_dword v181, v[10:11], off offset:-2816 nt
	global_load_dword v182, v[10:11], off offset:-2560 nt
	global_load_dword v183, v[10:11], off offset:-2304 nt
	global_load_dword v184, v[10:11], off offset:-2048 nt
	global_load_dword v185, v[10:11], off offset:-1792 nt
	global_load_dword v186, v[10:11], off offset:-1536 nt
	global_load_dword v187, v[10:11], off offset:-1280 nt
	global_load_dword v188, v[10:11], off offset:-1024 nt
	global_load_dword v189, v[10:11], off offset:-768 nt
	global_load_dword v190, v[10:11], off offset:-512 nt
	global_load_dword v191, v[10:11], off offset:-256 nt
	s_waitcnt vmcnt(32)
	v_pk_add_f32 v[96:97], v[96:97], v[198:199]
	v_pk_add_f32 v[98:99], v[98:99], v[200:201]
	v_pk_add_f32 v[100:101], v[100:101], v[202:203]
	v_pk_add_f32 v[102:103], v[102:103], v[204:205]
	v_pk_add_f32 v[104:105], v[104:105], v[206:207]
	v_pk_add_f32 v[106:107], v[106:107], v[208:209]
	v_pk_add_f32 v[108:109], v[108:109], v[210:211]
	v_pk_add_f32 v[110:111], v[110:111], v[212:213]
	global_load_dword v198, v[10:11], off nt
	global_load_dword v199, v[10:11], off offset:256 nt
	global_load_dword v200, v[10:11], off offset:512 nt
	global_load_dword v201, v[10:11], off offset:768 nt
	global_load_dword v202, v[10:11], off offset:1024 nt
	global_load_dword v203, v[10:11], off offset:1280 nt
	global_load_dword v204, v[10:11], off offset:1536 nt
	global_load_dword v205, v[10:11], off offset:1792 nt
	global_load_dword v206, v[10:11], off offset:2048 nt
	global_load_dword v207, v[10:11], off offset:2304 nt
	global_load_dword v208, v[10:11], off offset:2560 nt
	global_load_dword v209, v[10:11], off offset:2816 nt
	global_load_dword v210, v[10:11], off offset:3072 nt
	global_load_dword v211, v[10:11], off offset:3328 nt
	global_load_dword v212, v[10:11], off offset:3584 nt
	global_load_dword v213, v[10:11], off offset:3840 nt
	s_waitcnt vmcnt(32)
	v_pk_add_f32 v[80:81], v[80:81], v[160:161]
	v_pk_add_f32 v[82:83], v[82:83], v[162:163]
	v_pk_add_f32 v[84:85], v[84:85], v[164:165]
	v_pk_add_f32 v[86:87], v[86:87], v[166:167]
	v_pk_add_f32 v[88:89], v[88:89], v[168:169]
	v_pk_add_f32 v[90:91], v[90:91], v[170:171]
	v_pk_add_f32 v[92:93], v[92:93], v[172:173]
	v_pk_add_f32 v[94:95], v[94:95], v[174:175]
	global_load_dword v160, v[12:13], off offset:-4096 nt
	global_load_dword v161, v[12:13], off offset:-3840 nt
	global_load_dword v162, v[12:13], off offset:-3584 nt
	global_load_dword v163, v[12:13], off offset:-3328 nt
	global_load_dword v164, v[12:13], off offset:-3072 nt
	global_load_dword v165, v[12:13], off offset:-2816 nt
	global_load_dword v166, v[12:13], off offset:-2560 nt
	global_load_dword v167, v[12:13], off offset:-2304 nt
	global_load_dword v168, v[12:13], off offset:-2048 nt
	global_load_dword v169, v[12:13], off offset:-1792 nt
	global_load_dword v170, v[12:13], off offset:-1536 nt
	global_load_dword v171, v[12:13], off offset:-1280 nt
	global_load_dword v172, v[12:13], off offset:-1024 nt
	global_load_dword v173, v[12:13], off offset:-768 nt
	global_load_dword v174, v[12:13], off offset:-512 nt
	global_load_dword v175, v[12:13], off offset:-256 nt
	s_waitcnt vmcnt(32)
	v_pk_add_f32 v[64:65], v[64:65], v[176:177]
	v_pk_add_f32 v[66:67], v[66:67], v[178:179]
	v_pk_add_f32 v[68:69], v[68:69], v[180:181]
	v_pk_add_f32 v[70:71], v[70:71], v[182:183]
	v_pk_add_f32 v[72:73], v[72:73], v[184:185]
	v_pk_add_f32 v[74:75], v[74:75], v[186:187]
	v_pk_add_f32 v[76:77], v[76:77], v[188:189]
	v_pk_add_f32 v[78:79], v[78:79], v[190:191]
	global_load_dword v176, v[12:13], off nt
	global_load_dword v177, v[12:13], off offset:256 nt
	global_load_dword v178, v[12:13], off offset:512 nt
	global_load_dword v179, v[12:13], off offset:768 nt
	global_load_dword v180, v[12:13], off offset:1024 nt
	global_load_dword v181, v[12:13], off offset:1280 nt
	global_load_dword v182, v[12:13], off offset:1536 nt
	global_load_dword v183, v[12:13], off offset:1792 nt
	global_load_dword v184, v[12:13], off offset:2048 nt
	global_load_dword v185, v[12:13], off offset:2304 nt
	global_load_dword v186, v[12:13], off offset:2560 nt
	global_load_dword v187, v[12:13], off offset:2816 nt
	global_load_dword v188, v[12:13], off offset:3072 nt
	global_load_dword v189, v[12:13], off offset:3328 nt
	global_load_dword v190, v[12:13], off offset:3584 nt
	global_load_dword v191, v[12:13], off offset:3840 nt
	global_load_dword v5, v[2:3], off
	global_load_dword v4, v[2:3], off offset:256
	s_waitcnt vmcnt(34)
	v_pk_add_f32 v[48:49], v[48:49], v[198:199]
	v_pk_add_f32 v[50:51], v[50:51], v[200:201]
	v_pk_add_f32 v[52:53], v[52:53], v[202:203]
	v_pk_add_f32 v[54:55], v[54:55], v[204:205]
	v_pk_add_f32 v[56:57], v[56:57], v[206:207]
	v_pk_add_f32 v[58:59], v[58:59], v[208:209]
	v_pk_add_f32 v[60:61], v[60:61], v[210:211]
	v_pk_add_f32 v[62:63], v[62:63], v[212:213]
	s_waitcnt vmcnt(18)
	v_pk_add_f32 v[32:33], v[32:33], v[160:161]
	v_pk_add_f32 v[34:35], v[34:35], v[162:163]
	v_pk_add_f32 v[36:37], v[36:37], v[164:165]
	v_pk_add_f32 v[38:39], v[38:39], v[166:167]
	v_pk_add_f32 v[40:41], v[40:41], v[168:169]
	v_pk_add_f32 v[42:43], v[42:43], v[170:171]
	v_pk_add_f32 v[44:45], v[44:45], v[172:173]
	v_pk_add_f32 v[46:47], v[46:47], v[174:175]
	s_waitcnt vmcnt(2)
	v_pk_add_f32 v[16:17], v[16:17], v[176:177]
	v_pk_add_f32 v[18:19], v[18:19], v[178:179]
	v_pk_add_f32 v[20:21], v[20:21], v[180:181]
	v_pk_add_f32 v[22:23], v[22:23], v[182:183]
	v_pk_add_f32 v[24:25], v[24:25], v[184:185]
	v_pk_add_f32 v[26:27], v[26:27], v[186:187]
	v_pk_add_f32 v[28:29], v[28:29], v[188:189]
	v_pk_add_f32 v[30:31], v[30:31], v[190:191]
	s_waitcnt vmcnt(0)
	v_pk_add_f32 v[14:15], v[14:15], v[4:5]
	s_andn2_b64 vcc, exec, s[72:73]
	s_mov_b64 s[0:1], -1
	s_cbranch_vccz .LBB0_448

.LBB0_620:
	s_or_b64 exec, exec, s[10:11]
	v_cvt_f32_u32_e32 v4, v2
	s_waitcnt vmcnt(0)
	v_readfirstlane_b32 s2, v3
	v_sub_u32_e32 v3, 0, v2
	v_rcp_iflag_f32_e32 v4, v4
	v_add_u32_e32 v5, s2, v1
	v_mul_f32_e32 v4, 0x4f7ffffe, v4
	v_cvt_u32_f32_e32 v4, v4
	v_mul_lo_u32 v1, v3, v4
	v_mul_hi_u32 v1, v4, v1
	v_add_u32_e32 v1, v4, v1
	v_mul_hi_u32 v1, v5, v1
	v_mul_lo_u32 v3, v1, v2
	v_sub_u32_e32 v3, v5, v3
	v_add_u32_e32 v4, 1, v1
	v_cmp_ge_u32_e32 vcc, v3, v2
	s_nop 1
	v_cndmask_b32_e32 v1, v1, v4, vcc
	v_sub_u32_e32 v4, v3, v2
	v_cndmask_b32_e32 v3, v3, v4, vcc
	v_add_u32_e32 v4, 1, v1
	v_cmp_ge_u32_e32 vcc, v3, v2
	v_add_u32_e32 v3, 1, v5
	s_nop 0
	v_cndmask_b32_e32 v1, v1, v4, vcc
	v_mul_lo_u32 v4, v2, v1
	v_add_u32_e32 v2, v4, v2
	v_cmp_ne_u32_e32 vcc, v3, v2
	s_and_saveexec_b64 s[2:3], vcc
	s_xor_b64 s[8:9], exec, s[2:3]
	s_cbranch_execz .LBB0_634
	s_waitcnt lgkmcnt(0)
	v_mov_b32_e32 v0, 0x2000
	buffer_inv sc1
	global_load_dword v0, v0, s[6:7] offset:1024 sc1
	s_add_u32 s14, s6, 0x2400
	s_addc_u32 s15, s7, 0
	s_waitcnt vmcnt(0)
	v_cmp_eq_u32_e32 vcc, v0, v1
	s_and_saveexec_b64 s[10:11], vcc
	s_cbranch_execz .LBB0_633
	s_add_u32 s12, s74, 0xfa00200
	s_addc_u32 s13, s75, 0
	s_mov_b32 s2, 1
	s_mov_b64 s[16:17], 0
	v_mov_b32_e32 v0, 0
	s_branch .LBB0_624

.LBB0_633:
	s_or_b64 exec, exec, s[10:11]
	s_waitcnt vmcnt(0)
	s_waitcnt vmcnt(0)

.LBB0_637:
	s_or_b64 exec, exec, s[10:11]
	v_cvt_f32_u32_e32 v3, v0
	s_waitcnt vmcnt(0)
	buffer_inv sc1
	v_readfirstlane_b32 s2, v2
	s_add_u32 s10, s74, 0xfa03500
	s_addc_u32 s11, s75, 0
	v_rcp_iflag_f32_e32 v3, v3
	v_add_u32_e32 v1, s2, v1
	v_add_u32_e32 v4, 1, v1
	s_mov_b64 s[12:13], -1
	v_mul_f32_e32 v2, 0x4f7ffffe, v3
	v_cvt_u32_f32_e32 v2, v2
	v_sub_u32_e32 v3, 0, v0
	v_mul_lo_u32 v3, v3, v2
	v_mul_hi_u32 v3, v2, v3
	v_add_u32_e32 v2, v2, v3
	v_mul_hi_u32 v2, v1, v2
	v_mul_lo_u32 v3, v2, v0
	v_sub_u32_e32 v1, v1, v3
	v_add_u32_e32 v5, 1, v2
	v_cmp_ge_u32_e32 vcc, v1, v0
	v_sub_u32_e32 v3, v1, v0
	s_nop 0
	v_cndmask_b32_e32 v2, v2, v5, vcc
	v_cndmask_b32_e32 v1, v1, v3, vcc
	v_add_u32_e32 v3, 1, v2
	v_cmp_ge_u32_e32 vcc, v1, v0
	s_nop 1
	v_cndmask_b32_e32 v2, v2, v3, vcc
	v_mul_lo_u32 v1, v0, v2
	v_add_u32_e32 v0, v1, v0
	v_cmp_ne_u32_e32 vcc, v4, v0
	v_mov_b64_e32 v[0:1], s[10:11]
	s_and_saveexec_b64 s[8:9], vcc
	s_cbranch_execz .LBB0_649
	v_mov_b32_e32 v0, 0
	global_load_dword v1, v0, s[10:11] sc1
	s_mov_b64 s[16:17], 0
	s_waitcnt vmcnt(0)
	v_cmp_eq_u32_e32 vcc, v1, v2
	s_and_saveexec_b64 s[14:15], vcc
	s_cbranch_execz .LBB0_648
	s_add_u32 s12, s74, 0xfa00200
	s_addc_u32 s13, s75, 0
	s_mov_b32 s2, 1
	s_branch .LBB0_641

.LBB0_651:
	s_or_b64 exec, exec, s[8:9]
	s_mov_b64 s[8:9], exec
	v_mbcnt_lo_u32_b32 v0, s8, 0
	v_mbcnt_hi_u32_b32 v0, s9, v0
	v_cmp_eq_u32_e32 vcc, 0, v0
	s_waitcnt vmcnt(0)
	s_and_saveexec_b64 s[10:11], vcc
	s_cbranch_execz .LBB0_653
	s_bcnt1_i32_b64 s2, s[8:9]
	v_mov_b32_e32 v0, 0x2000
	v_mov_b32_e32 v1, s2
	global_atomic_add v0, v1, s[6:7] offset:1024

.LBB0_863:
	s_or_b64 exec, exec, s[8:9]
	v_cvt_f32_u32_e32 v4, v2
	s_waitcnt vmcnt(0)
	v_readfirstlane_b32 s6, v3
	v_sub_u32_e32 v3, 0, v2
	v_rcp_iflag_f32_e32 v4, v4
	v_add_u32_e32 v5, s6, v1
	v_mul_f32_e32 v4, 0x4f7ffffe, v4
	v_cvt_u32_f32_e32 v4, v4
	v_mul_lo_u32 v1, v3, v4
	v_mul_hi_u32 v1, v4, v1
	v_add_u32_e32 v1, v4, v1
	v_mul_hi_u32 v1, v5, v1
	v_mul_lo_u32 v3, v1, v2
	v_sub_u32_e32 v3, v5, v3
	v_add_u32_e32 v4, 1, v1
	v_cmp_ge_u32_e32 vcc, v3, v2
	s_nop 1
	v_cndmask_b32_e32 v1, v1, v4, vcc
	v_sub_u32_e32 v4, v3, v2
	v_cndmask_b32_e32 v3, v3, v4, vcc
	v_add_u32_e32 v4, 1, v1
	v_cmp_ge_u32_e32 vcc, v3, v2
	v_add_u32_e32 v3, 1, v5
	s_nop 0
	v_cndmask_b32_e32 v1, v1, v4, vcc
	v_mul_lo_u32 v4, v2, v1
	v_add_u32_e32 v2, v4, v2
	v_cmp_ne_u32_e32 vcc, v3, v2
	s_and_saveexec_b64 s[6:7], vcc
	s_xor_b64 s[6:7], exec, s[6:7]
	s_cbranch_execz .LBB0_877
	s_waitcnt lgkmcnt(0)
	v_mov_b32_e32 v0, 0x2000
	buffer_inv sc1
	global_load_dword v0, v0, s[4:5] offset:1024 sc1
	s_add_u32 s12, s4, 0x2400
	s_addc_u32 s13, s5, 0
	s_waitcnt vmcnt(0)
	v_cmp_eq_u32_e32 vcc, v0, v1
	s_and_saveexec_b64 s[8:9], vcc
	s_cbranch_execz .LBB0_876
	s_add_u32 s10, s74, 0xfa00200
	s_addc_u32 s11, s75, 0
	s_mov_b32 s24, 1
	s_mov_b64 s[14:15], 0
	v_mov_b32_e32 v0, 0
	s_branch .LBB0_867

.LBB0_880:
	s_or_b64 exec, exec, s[8:9]
	v_cvt_f32_u32_e32 v3, v0
	s_waitcnt vmcnt(0)
	buffer_inv sc1
	v_readfirstlane_b32 s6, v2
	s_add_u32 s8, s74, 0xfa03500
	s_addc_u32 s9, s75, 0
	v_rcp_iflag_f32_e32 v3, v3
	v_add_u32_e32 v1, s6, v1
	v_add_u32_e32 v4, 1, v1
	s_mov_b64 s[10:11], -1
	v_mul_f32_e32 v2, 0x4f7ffffe, v3
	v_cvt_u32_f32_e32 v2, v2
	v_sub_u32_e32 v3, 0, v0
	v_mul_lo_u32 v3, v3, v2
	v_mul_hi_u32 v3, v2, v3
	v_add_u32_e32 v2, v2, v3
	v_mul_hi_u32 v2, v1, v2
	v_mul_lo_u32 v3, v2, v0
	v_sub_u32_e32 v1, v1, v3
	v_add_u32_e32 v5, 1, v2
	v_cmp_ge_u32_e32 vcc, v1, v0
	v_sub_u32_e32 v3, v1, v0
	s_nop 0
	v_cndmask_b32_e32 v2, v2, v5, vcc
	v_cndmask_b32_e32 v1, v1, v3, vcc
	v_add_u32_e32 v3, 1, v2
	v_cmp_ge_u32_e32 vcc, v1, v0
	s_nop 1
	v_cndmask_b32_e32 v2, v2, v3, vcc
	v_mul_lo_u32 v1, v0, v2
	v_add_u32_e32 v0, v1, v0
	v_cmp_ne_u32_e32 vcc, v4, v0
	v_mov_b64_e32 v[0:1], s[8:9]
	s_and_saveexec_b64 s[6:7], vcc
	s_cbranch_execz .LBB0_892
	v_mov_b32_e32 v0, 0
	global_load_dword v1, v0, s[8:9] sc1
	s_mov_b64 s[14:15], 0
	s_waitcnt vmcnt(0)
	v_cmp_eq_u32_e32 vcc, v1, v2
	s_and_saveexec_b64 s[12:13], vcc
	s_cbranch_execz .LBB0_891
	s_add_u32 s10, s74, 0xfa00200
	s_addc_u32 s11, s75, 0
	s_mov_b32 s24, 1
	s_branch .LBB0_884

.LBB0_894:
	s_or_b64 exec, exec, s[6:7]
	s_mov_b64 s[6:7], exec
	v_mbcnt_lo_u32_b32 v0, s6, 0
	v_mbcnt_hi_u32_b32 v0, s7, v0
	v_cmp_eq_u32_e32 vcc, 0, v0
	s_waitcnt vmcnt(0)
	s_and_saveexec_b64 s[8:9], vcc
	s_cbranch_execz .LBB0_896
	s_bcnt1_i32_b64 s6, s[6:7]
	v_mov_b32_e32 v0, 0x2000
	v_mov_b32_e32 v1, s6
	global_atomic_add v0, v1, s[4:5] offset:1024

.LBB0_959:
	s_or_b64 exec, exec, s[10:11]
	v_cvt_f32_u32_e32 v4, v2
	s_waitcnt vmcnt(0)
	v_readfirstlane_b32 s2, v3
	v_sub_u32_e32 v3, 0, v2
	v_rcp_iflag_f32_e32 v4, v4
	v_add_u32_e32 v5, s2, v1
	v_mul_f32_e32 v4, 0x4f7ffffe, v4
	v_cvt_u32_f32_e32 v4, v4
	v_mul_lo_u32 v1, v3, v4
	v_mul_hi_u32 v1, v4, v1
	v_add_u32_e32 v1, v4, v1
	v_mul_hi_u32 v1, v5, v1
	v_mul_lo_u32 v3, v1, v2
	v_sub_u32_e32 v3, v5, v3
	v_add_u32_e32 v4, 1, v1
	v_cmp_ge_u32_e32 vcc, v3, v2
	s_nop 1
	v_cndmask_b32_e32 v1, v1, v4, vcc
	v_sub_u32_e32 v4, v3, v2
	v_cndmask_b32_e32 v3, v3, v4, vcc
	v_add_u32_e32 v4, 1, v1
	v_cmp_ge_u32_e32 vcc, v3, v2
	v_add_u32_e32 v3, 1, v5
	s_nop 0
	v_cndmask_b32_e32 v1, v1, v4, vcc
	v_mul_lo_u32 v4, v2, v1
	v_add_u32_e32 v2, v4, v2
	v_cmp_ne_u32_e32 vcc, v3, v2
	s_and_saveexec_b64 s[2:3], vcc
	s_xor_b64 s[6:7], exec, s[2:3]
	s_cbranch_execz .LBB0_973
	s_waitcnt lgkmcnt(0)
	v_mov_b32_e32 v0, 0x2000
	buffer_inv sc1
	global_load_dword v0, v0, s[4:5] offset:1024 sc1
	s_add_u32 s14, s4, 0x2400
	s_addc_u32 s15, s5, 0
	s_waitcnt vmcnt(0)
	v_cmp_eq_u32_e32 vcc, v0, v1
	s_and_saveexec_b64 s[10:11], vcc
	s_cbranch_execz .LBB0_972
	s_add_u32 s12, s74, 0xfa00200
	s_addc_u32 s13, s75, 0
	s_mov_b32 s2, 1
	s_mov_b64 s[16:17], 0
	v_mov_b32_e32 v0, 0
	s_branch .LBB0_963

.LBB0_976:
	s_or_b64 exec, exec, s[10:11]
	v_cvt_f32_u32_e32 v3, v0
	s_waitcnt vmcnt(0)
	buffer_inv sc1
	v_readfirstlane_b32 s2, v2
	s_add_u32 s10, s74, 0xfa03500
	s_addc_u32 s11, s75, 0
	v_rcp_iflag_f32_e32 v3, v3
	v_add_u32_e32 v1, s2, v1
	v_add_u32_e32 v4, 1, v1
	s_mov_b64 s[12:13], -1
	v_mul_f32_e32 v2, 0x4f7ffffe, v3
	v_cvt_u32_f32_e32 v2, v2
	v_sub_u32_e32 v3, 0, v0
	v_mul_lo_u32 v3, v3, v2
	v_mul_hi_u32 v3, v2, v3
	v_add_u32_e32 v2, v2, v3
	v_mul_hi_u32 v2, v1, v2
	v_mul_lo_u32 v3, v2, v0
	v_sub_u32_e32 v1, v1, v3
	v_add_u32_e32 v5, 1, v2
	v_cmp_ge_u32_e32 vcc, v1, v0
	v_sub_u32_e32 v3, v1, v0
	s_nop 0
	v_cndmask_b32_e32 v2, v2, v5, vcc
	v_cndmask_b32_e32 v1, v1, v3, vcc
	v_add_u32_e32 v3, 1, v2
	v_cmp_ge_u32_e32 vcc, v1, v0
	s_nop 1
	v_cndmask_b32_e32 v2, v2, v3, vcc
	v_mul_lo_u32 v1, v0, v2
	v_add_u32_e32 v0, v1, v0
	v_cmp_ne_u32_e32 vcc, v4, v0
	v_mov_b64_e32 v[0:1], s[10:11]
	s_and_saveexec_b64 s[6:7], vcc
	s_cbranch_execz .LBB0_988
	v_mov_b32_e32 v0, 0
	global_load_dword v1, v0, s[10:11] sc1
	s_mov_b64 s[16:17], 0
	s_waitcnt vmcnt(0)
	v_cmp_eq_u32_e32 vcc, v1, v2
	s_and_saveexec_b64 s[14:15], vcc
	s_cbranch_execz .LBB0_987
	s_add_u32 s12, s74, 0xfa00200
	s_addc_u32 s13, s75, 0
	s_mov_b32 s2, 1
	s_branch .LBB0_980

.LBB0_990:
	s_or_b64 exec, exec, s[6:7]
	s_mov_b64 s[6:7], exec
	v_mbcnt_lo_u32_b32 v0, s6, 0
	v_mbcnt_hi_u32_b32 v0, s7, v0
	v_cmp_eq_u32_e32 vcc, 0, v0
	s_waitcnt vmcnt(0)
	s_and_saveexec_b64 s[10:11], vcc
	s_cbranch_execz .LBB0_992
	s_bcnt1_i32_b64 s2, s[6:7]
	v_mov_b32_e32 v0, 0x2000
	v_mov_b32_e32 v1, s2
	global_atomic_add v0, v1, s[4:5] offset:1024

.LBB0_1006:
	v_lshl_add_u32 v144, s0, 8, v148
	v_ashrrev_i32_e32 v145, 31, v144
	v_lshl_add_u64 v[146:147], v[144:145], 2, s[8:9]
	global_load_dword v145, v[146:147], off
	global_load_dword v171, v[146:147], off offset:64
	global_load_dword v172, v[146:147], off offset:128
	global_load_dword v173, v[146:147], off offset:192
	global_load_dword v174, v[146:147], off offset:512
	global_load_dword v175, v[146:147], off offset:576
	global_load_dword v176, v[146:147], off offset:640
	global_load_dword v177, v[146:147], off offset:704
	v_lshl_add_u32 v156, s1, 7, v150
	v_readlane_b32 s0, v255, 0
	v_mov_b32_e32 v161, v114
	v_mov_b32_e32 v114, v123
	v_readlane_b32 s1, v255, 1
	v_mov_b32_e32 v158, v124
	v_mov_b32_e32 v159, v116
	v_mov_b32_e32 v116, v125
	v_mov_b32_e32 v124, v126
	v_mov_b32_e32 v125, v118
	v_mov_b32_e32 v118, v127
	v_mov_b32_e32 v126, v120
	v_mov_b32_e32 v127, v112
	v_mov_b32_e32 v112, v121
	v_mov_b32_e32 v160, v122
	v_mov_b64_e32 v[120:121], s[0:1]
	v_ashrrev_i32_e32 v157, 31, v156
	v_or_b32_e32 v164, 16, v144
	v_mad_i64_i32 v[162:163], s[0:1], v144, s41, v[120:121]
	v_lshlrev_b64 v[122:123], 1, v[156:157]
	v_ashrrev_i32_e32 v165, 31, v164
	v_lshl_add_u64 v[156:157], v[162:163], 0, v[122:123]
	v_lshl_add_u64 v[162:163], v[164:165], 2, s[8:9]
	s_waitcnt vmcnt(0)
	v_fmamk_f32 v145, v145, 0x3a800000, v154
	v_mul_f32_e32 v155, 0x4b800000, v145
	v_cmp_gt_f32_e32 vcc, s40, v145
	s_nop 1
	v_cndmask_b32_e32 v145, v145, v155, vcc
	v_rsq_f32_e32 v145, v145
	s_nop 0
	v_mul_f32_e32 v155, 0x45800000, v145
	v_cndmask_b32_e32 v166, v145, v155, vcc
	v_pk_mul_f32 v[114:115], v[114:115], v[166:167] op_sel_hi:[1,0]
	v_pk_mul_f32 v[158:159], v[158:159], v[166:167] op_sel_hi:[1,0]
	v_pk_mul_f32 v[116:117], v[116:117], v[166:167] op_sel_hi:[1,0]
	v_pk_mul_f32 v[124:125], v[124:125], v[166:167] op_sel_hi:[1,0]
	v_pk_mul_f32 v[118:119], v[118:119], v[166:167] op_sel_hi:[1,0]
	v_pk_mul_f32 v[126:127], v[126:127], v[166:167] op_sel_hi:[1,0]
	v_pk_mul_f32 v[112:113], v[112:113], v[166:167] op_sel_hi:[1,0]
	v_pk_mul_f32 v[160:161], v[160:161], v[166:167] op_sel_hi:[1,0]
	v_mul_f32_e32 v170, 0xbfb8aa3b, v115
	v_mul_f32_e32 v145, 0xbfb8aa3b, v159
	v_mul_f32_e32 v155, 0xbfb8aa3b, v117
	v_mul_f32_e32 v165, 0xbfb8aa3b, v125
	v_mul_f32_e32 v166, 0xbfb8aa3b, v119
	v_mul_f32_e32 v167, 0xbfb8aa3b, v127
	v_mul_f32_e32 v168, 0xbfb8aa3b, v113
	v_mul_f32_e32 v169, 0xbfb8aa3b, v161
	v_exp_f32_e32 v170, v170
	v_exp_f32_e32 v145, v145
	v_exp_f32_e32 v155, v155
	v_exp_f32_e32 v165, v165
	v_exp_f32_e32 v166, v166
	v_exp_f32_e32 v167, v167
	v_exp_f32_e32 v168, v168
	v_exp_f32_e32 v169, v169
	v_add_f32_e32 v170, 1.0, v170
	v_add_f32_e32 v145, 1.0, v145
	v_add_f32_e32 v155, 1.0, v155
	v_add_f32_e32 v165, 1.0, v165
	v_add_f32_e32 v166, 1.0, v166
	v_add_f32_e32 v167, 1.0, v167
	v_add_f32_e32 v168, 1.0, v168
	v_add_f32_e32 v169, 1.0, v169
	v_rcp_f32_e32 v170, v170
	v_rcp_f32_e32 v145, v145
	v_rcp_f32_e32 v155, v155
	v_rcp_f32_e32 v165, v165
	v_rcp_f32_e32 v166, v166
	v_rcp_f32_e32 v167, v167
	v_rcp_f32_e32 v168, v168
	v_rcp_f32_e32 v169, v169
	v_mul_f32_e32 v115, v115, v170
	v_mul_f32_e32 v145, v159, v145
	v_mul_f32_e32 v117, v117, v155
	v_mul_f32_e32 v125, v125, v165
	v_mul_f32_e32 v119, v119, v166
	v_mul_f32_e32 v127, v127, v167
	v_mul_f32_e32 v113, v113, v168
	v_mul_f32_e32 v155, v161, v169
	v_mul_f32_e32 v115, v114, v115
	v_mul_f32_e32 v145, v158, v145
	v_mul_f32_e32 v116, v116, v117
	v_mul_f32_e32 v117, v124, v125
	v_mul_f32_e32 v118, v118, v119
	v_mul_f32_e32 v119, v126, v127
	v_mul_f32_e32 v124, v112, v113
	v_mul_f32_e32 v125, v160, v155
	v_cvt_pk_bf16_f32 v112, v145, v116
	v_cvt_pk_bf16_f32 v113, v117, v118
	v_cvt_pk_bf16_f32 v114, v119, v124
	v_cvt_pk_bf16_f32 v115, v125, v115
	global_store_dwordx4 v[156:157], v[112:115], off
	s_nop 0
	s_nop 0
	v_mov_b32_e32 v113, v100
	v_mov_b32_e32 v100, v109
	v_mov_b32_e32 v109, v102
	v_mov_b32_e32 v102, v111
	v_mov_b32_e32 v111, v96
	v_mov_b32_e32 v96, v105
	v_mov_b32_e32 v105, v98
	v_mov_b32_e32 v98, v107
	v_mov_b32_e32 v112, v108
	v_mov_b32_e32 v108, v110
	v_mov_b32_e32 v110, v104
	v_mov_b32_e32 v104, v106
	v_or_b32_e32 v106, 32, v144
	v_mad_i64_i32 v[114:115], s[0:1], v164, s41, v[120:121]
	v_lshl_add_u64 v[114:115], v[114:115], 0, v[122:123]
	s_nop 0
	v_fmamk_f32 v107, v171, 0x3a800000, v154
	v_mul_f32_e32 v116, 0x4b800000, v107
	v_cmp_gt_f32_e32 vcc, s40, v107
	s_nop 1
	v_cndmask_b32_e32 v107, v107, v116, vcc
	v_rsq_f32_e32 v118, v107
	v_ashrrev_i32_e32 v107, 31, v106
	v_lshl_add_u64 v[116:117], v[106:107], 2, s[8:9]
	v_mul_f32_e32 v107, 0x45800000, v118
	v_cndmask_b32_e32 v118, v118, v107, vcc
	v_pk_mul_f32 v[98:99], v[98:99], v[118:119] op_sel_hi:[1,0]
	v_pk_mul_f32 v[112:113], v[112:113], v[118:119] op_sel_hi:[1,0]
	v_pk_mul_f32 v[100:101], v[100:101], v[118:119] op_sel_hi:[1,0]
	v_pk_mul_f32 v[108:109], v[108:109], v[118:119] op_sel_hi:[1,0]
	v_pk_mul_f32 v[102:103], v[102:103], v[118:119] op_sel_hi:[1,0]
	v_pk_mul_f32 v[110:111], v[110:111], v[118:119] op_sel_hi:[1,0]
	v_pk_mul_f32 v[96:97], v[96:97], v[118:119] op_sel_hi:[1,0]
	v_pk_mul_f32 v[104:105], v[104:105], v[118:119] op_sel_hi:[1,0]
	v_mul_f32_e32 v145, 0xbfb8aa3b, v99
	v_mul_f32_e32 v107, 0xbfb8aa3b, v113
	v_mul_f32_e32 v118, 0xbfb8aa3b, v101
	v_mul_f32_e32 v119, 0xbfb8aa3b, v109
	v_mul_f32_e32 v124, 0xbfb8aa3b, v103
	v_mul_f32_e32 v125, 0xbfb8aa3b, v111
	v_mul_f32_e32 v126, 0xbfb8aa3b, v97
	v_mul_f32_e32 v127, 0xbfb8aa3b, v105
	v_exp_f32_e32 v145, v145
	v_exp_f32_e32 v107, v107
	v_exp_f32_e32 v118, v118
	v_exp_f32_e32 v119, v119
	v_exp_f32_e32 v124, v124
	v_exp_f32_e32 v125, v125
	v_exp_f32_e32 v126, v126
	v_exp_f32_e32 v127, v127
	v_add_f32_e32 v145, 1.0, v145
	v_add_f32_e32 v107, 1.0, v107
	v_add_f32_e32 v118, 1.0, v118
	v_add_f32_e32 v119, 1.0, v119
	v_add_f32_e32 v124, 1.0, v124
	v_add_f32_e32 v125, 1.0, v125
	v_add_f32_e32 v126, 1.0, v126
	v_add_f32_e32 v127, 1.0, v127
	v_rcp_f32_e32 v145, v145
	v_rcp_f32_e32 v107, v107
	v_rcp_f32_e32 v118, v118
	v_rcp_f32_e32 v119, v119
	v_rcp_f32_e32 v124, v124
	v_rcp_f32_e32 v125, v125
	v_rcp_f32_e32 v126, v126
	v_rcp_f32_e32 v127, v127
	v_mul_f32_e32 v99, v99, v145
	v_mul_f32_e32 v107, v113, v107
	v_mul_f32_e32 v101, v101, v118
	v_mul_f32_e32 v109, v109, v119
	v_mul_f32_e32 v103, v103, v124
	v_mul_f32_e32 v111, v111, v125
	v_mul_f32_e32 v97, v97, v126
	v_mul_f32_e32 v105, v105, v127
	v_mul_f32_e32 v99, v98, v99
	v_mul_f32_e32 v107, v112, v107
	v_mul_f32_e32 v100, v100, v101
	v_mul_f32_e32 v101, v108, v109
	v_mul_f32_e32 v102, v102, v103
	v_mul_f32_e32 v103, v110, v111
	v_mul_f32_e32 v108, v96, v97
	v_mul_f32_e32 v104, v104, v105
	v_cvt_pk_bf16_f32 v96, v107, v100
	v_cvt_pk_bf16_f32 v97, v101, v102
	v_cvt_pk_bf16_f32 v98, v103, v108
	v_cvt_pk_bf16_f32 v99, v104, v99
	global_store_dwordx4 v[114:115], v[96:99], off
	s_nop 0
	s_nop 0
	v_mov_b32_e32 v97, v84
	v_mov_b32_e32 v84, v93
	v_mov_b32_e32 v93, v86
	v_mov_b32_e32 v86, v95
	v_mov_b32_e32 v95, v80
	v_mov_b32_e32 v80, v89
	v_mov_b32_e32 v89, v82
	v_mov_b32_e32 v82, v91
	v_mov_b32_e32 v96, v92
	v_mov_b32_e32 v92, v94
	v_mov_b32_e32 v94, v88
	v_mov_b32_e32 v88, v90
	v_or_b32_e32 v90, 48, v144
	v_mad_i64_i32 v[98:99], s[0:1], v106, s41, v[120:121]
	v_lshl_add_u64 v[98:99], v[98:99], 0, v[122:123]
	s_nop 0
	v_fmamk_f32 v91, v172, 0x3a800000, v154
	v_mul_f32_e32 v100, 0x4b800000, v91
	v_cmp_gt_f32_e32 vcc, s40, v91
	s_nop 1
	v_cndmask_b32_e32 v91, v91, v100, vcc
	v_rsq_f32_e32 v102, v91
	v_ashrrev_i32_e32 v91, 31, v90
	v_lshl_add_u64 v[100:101], v[90:91], 2, s[8:9]
	v_mul_f32_e32 v91, 0x45800000, v102
	v_cndmask_b32_e32 v102, v102, v91, vcc
	v_pk_mul_f32 v[82:83], v[82:83], v[102:103] op_sel_hi:[1,0]
	v_pk_mul_f32 v[96:97], v[96:97], v[102:103] op_sel_hi:[1,0]
	v_pk_mul_f32 v[84:85], v[84:85], v[102:103] op_sel_hi:[1,0]
	v_pk_mul_f32 v[92:93], v[92:93], v[102:103] op_sel_hi:[1,0]
	v_pk_mul_f32 v[86:87], v[86:87], v[102:103] op_sel_hi:[1,0]
	v_pk_mul_f32 v[94:95], v[94:95], v[102:103] op_sel_hi:[1,0]
	v_pk_mul_f32 v[80:81], v[80:81], v[102:103] op_sel_hi:[1,0]
	v_pk_mul_f32 v[88:89], v[88:89], v[102:103] op_sel_hi:[1,0]
	v_mul_f32_e32 v108, 0xbfb8aa3b, v83
	v_mul_f32_e32 v91, 0xbfb8aa3b, v97
	v_mul_f32_e32 v102, 0xbfb8aa3b, v85
	v_mul_f32_e32 v103, 0xbfb8aa3b, v93
	v_mul_f32_e32 v104, 0xbfb8aa3b, v87
	v_mul_f32_e32 v105, 0xbfb8aa3b, v95
	v_mul_f32_e32 v106, 0xbfb8aa3b, v81
	v_mul_f32_e32 v107, 0xbfb8aa3b, v89
	v_exp_f32_e32 v108, v108
	v_exp_f32_e32 v91, v91
	v_exp_f32_e32 v102, v102
	v_exp_f32_e32 v103, v103
	v_exp_f32_e32 v104, v104
	v_exp_f32_e32 v105, v105
	v_exp_f32_e32 v106, v106
	v_exp_f32_e32 v107, v107
	v_add_f32_e32 v108, 1.0, v108
	v_add_f32_e32 v91, 1.0, v91
	v_add_f32_e32 v102, 1.0, v102
	v_add_f32_e32 v103, 1.0, v103
	v_add_f32_e32 v104, 1.0, v104
	v_add_f32_e32 v105, 1.0, v105
	v_add_f32_e32 v106, 1.0, v106
	v_add_f32_e32 v107, 1.0, v107
	v_rcp_f32_e32 v108, v108
	v_rcp_f32_e32 v91, v91
	v_rcp_f32_e32 v102, v102
	v_rcp_f32_e32 v103, v103
	v_rcp_f32_e32 v104, v104
	v_rcp_f32_e32 v105, v105
	v_rcp_f32_e32 v106, v106
	v_rcp_f32_e32 v107, v107
	v_mul_f32_e32 v83, v83, v108
	v_mul_f32_e32 v91, v97, v91
	v_mul_f32_e32 v85, v85, v102
	v_mul_f32_e32 v93, v93, v103
	v_mul_f32_e32 v87, v87, v104
	v_mul_f32_e32 v95, v95, v105
	v_mul_f32_e32 v81, v81, v106
	v_mul_f32_e32 v89, v89, v107
	v_mul_f32_e32 v83, v82, v83
	v_mul_f32_e32 v91, v96, v91
	v_mul_f32_e32 v84, v84, v85
	v_mul_f32_e32 v85, v92, v93
	v_mul_f32_e32 v86, v86, v87
	v_mul_f32_e32 v87, v94, v95
	v_mul_f32_e32 v92, v80, v81
	v_mul_f32_e32 v88, v88, v89
	v_cvt_pk_bf16_f32 v80, v91, v84
	v_cvt_pk_bf16_f32 v81, v85, v86
	v_cvt_pk_bf16_f32 v82, v87, v92
	v_cvt_pk_bf16_f32 v83, v88, v83
	global_store_dwordx4 v[98:99], v[80:83], off
	s_nop 0
	s_nop 0
	v_mov_b32_e32 v80, v76
	v_mov_b32_e32 v76, v78
	v_mov_b32_e32 v78, v68
	v_mov_b32_e32 v68, v70
	v_mov_b32_e32 v81, v72
	v_mov_b32_e32 v72, v77
	v_mov_b32_e32 v77, v74
	v_mov_b32_e32 v74, v79
	v_mov_b32_e32 v79, v64
	v_mov_b32_e32 v64, v69
	v_mov_b32_e32 v69, v66
	v_mov_b32_e32 v66, v71
	s_nop 0
	v_fmamk_f32 v70, v173, 0x3a800000, v154
	v_mul_f32_e32 v71, 0x4b800000, v70
	v_cmp_gt_f32_e32 vcc, s40, v70
	s_nop 1
	v_cndmask_b32_e32 v70, v70, v71, vcc
	v_rsq_f32_e32 v82, v70
	v_mad_i64_i32 v[70:71], s[0:1], v90, s41, v[120:121]
	v_lshl_add_u64 v[70:71], v[70:71], 0, v[122:123]
	v_mul_f32_e32 v83, 0x45800000, v82
	v_cndmask_b32_e32 v82, v82, v83, vcc
	v_pk_mul_f32 v[66:67], v[66:67], v[82:83] op_sel_hi:[1,0]
	v_pk_mul_f32 v[80:81], v[80:81], v[82:83] op_sel_hi:[1,0]
	v_pk_mul_f32 v[72:73], v[72:73], v[82:83] op_sel_hi:[1,0]
	v_pk_mul_f32 v[76:77], v[76:77], v[82:83] op_sel_hi:[1,0]
	v_pk_mul_f32 v[74:75], v[74:75], v[82:83] op_sel_hi:[1,0]
	v_pk_mul_f32 v[78:79], v[78:79], v[82:83] op_sel_hi:[1,0]
	v_pk_mul_f32 v[64:65], v[64:65], v[82:83] op_sel_hi:[1,0]
	v_pk_mul_f32 v[68:69], v[68:69], v[82:83] op_sel_hi:[1,0]
	v_mul_f32_e32 v89, 0xbfb8aa3b, v67
	v_mul_f32_e32 v82, 0xbfb8aa3b, v81
	v_mul_f32_e32 v83, 0xbfb8aa3b, v73
	v_mul_f32_e32 v84, 0xbfb8aa3b, v77
	v_mul_f32_e32 v85, 0xbfb8aa3b, v75
	v_mul_f32_e32 v86, 0xbfb8aa3b, v79
	v_mul_f32_e32 v87, 0xbfb8aa3b, v65
	v_mul_f32_e32 v88, 0xbfb8aa3b, v69
	v_exp_f32_e32 v89, v89
	v_exp_f32_e32 v82, v82
	v_exp_f32_e32 v83, v83
	v_exp_f32_e32 v84, v84
	v_exp_f32_e32 v85, v85
	v_exp_f32_e32 v86, v86
	v_exp_f32_e32 v87, v87
	v_exp_f32_e32 v88, v88
	v_add_f32_e32 v89, 1.0, v89
	v_add_f32_e32 v82, 1.0, v82
	v_add_f32_e32 v83, 1.0, v83
	v_add_f32_e32 v84, 1.0, v84
	v_add_f32_e32 v85, 1.0, v85
	v_add_f32_e32 v86, 1.0, v86
	v_add_f32_e32 v87, 1.0, v87
	v_add_f32_e32 v88, 1.0, v88
	v_rcp_f32_e32 v89, v89
	v_rcp_f32_e32 v82, v82
	v_rcp_f32_e32 v83, v83
	v_rcp_f32_e32 v84, v84
	v_rcp_f32_e32 v85, v85
	v_rcp_f32_e32 v86, v86
	v_rcp_f32_e32 v87, v87
	v_rcp_f32_e32 v88, v88
	v_mul_f32_e32 v67, v67, v89
	v_mul_f32_e32 v81, v81, v82
	v_mul_f32_e32 v73, v73, v83
	v_mul_f32_e32 v77, v77, v84
	v_mul_f32_e32 v75, v75, v85
	v_mul_f32_e32 v79, v79, v86
	v_mul_f32_e32 v65, v65, v87
	v_mul_f32_e32 v69, v69, v88
	v_mul_f32_e32 v67, v66, v67
	v_mul_f32_e32 v80, v80, v81
	v_mul_f32_e32 v72, v72, v73
	v_mul_f32_e32 v73, v76, v77
	v_mul_f32_e32 v74, v74, v75
	v_mul_f32_e32 v75, v78, v79
	v_mul_f32_e32 v76, v64, v65
	v_mul_f32_e32 v68, v68, v69
	v_cvt_pk_bf16_f32 v64, v80, v72
	v_cvt_pk_bf16_f32 v65, v73, v74
	v_cvt_pk_bf16_f32 v66, v75, v76
	v_cvt_pk_bf16_f32 v67, v68, v67
	global_store_dwordx4 v[70:71], v[64:67], off
	s_nop 0
	s_nop 0
	v_mov_b32_e32 v65, v56
	v_mov_b32_e32 v56, v61
	v_mov_b32_e32 v61, v58
	v_mov_b32_e32 v58, v63
	v_mov_b32_e32 v63, v48
	v_mov_b32_e32 v48, v53
	v_mov_b32_e32 v53, v50
	v_mov_b32_e32 v50, v55
	v_mov_b32_e32 v64, v60
	v_mov_b32_e32 v60, v62
	v_mov_b32_e32 v62, v52
	v_mov_b32_e32 v52, v54
	v_add_u32_e32 v54, 0x80, v144
	s_nop 0
	v_fmamk_f32 v55, v174, 0x3a800000, v154
	v_mul_f32_e32 v66, 0x4b800000, v55
	v_cmp_gt_f32_e32 vcc, s40, v55
	s_nop 1
	v_cndmask_b32_e32 v55, v55, v66, vcc
	v_rsq_f32_e32 v66, v55
	v_mad_i64_i32 v[54:55], s[0:1], v54, s41, v[120:121]
	v_lshl_add_u64 v[54:55], v[54:55], 0, v[122:123]
	v_mul_f32_e32 v67, 0x45800000, v66
	v_cndmask_b32_e32 v66, v66, v67, vcc
	v_pk_mul_f32 v[50:51], v[50:51], v[66:67] op_sel_hi:[1,0]
	v_pk_mul_f32 v[64:65], v[64:65], v[66:67] op_sel_hi:[1,0]
	v_pk_mul_f32 v[56:57], v[56:57], v[66:67] op_sel_hi:[1,0]
	v_pk_mul_f32 v[60:61], v[60:61], v[66:67] op_sel_hi:[1,0]
	v_pk_mul_f32 v[58:59], v[58:59], v[66:67] op_sel_hi:[1,0]
	v_pk_mul_f32 v[62:63], v[62:63], v[66:67] op_sel_hi:[1,0]
	v_pk_mul_f32 v[48:49], v[48:49], v[66:67] op_sel_hi:[1,0]
	v_pk_mul_f32 v[52:53], v[52:53], v[66:67] op_sel_hi:[1,0]
	v_mul_f32_e32 v73, 0xbfb8aa3b, v51
	v_mul_f32_e32 v66, 0xbfb8aa3b, v65
	v_mul_f32_e32 v67, 0xbfb8aa3b, v57
	v_mul_f32_e32 v68, 0xbfb8aa3b, v61
	v_mul_f32_e32 v69, 0xbfb8aa3b, v59
	v_mul_f32_e32 v70, 0xbfb8aa3b, v63
	v_mul_f32_e32 v71, 0xbfb8aa3b, v49
	v_mul_f32_e32 v72, 0xbfb8aa3b, v53
	v_exp_f32_e32 v73, v73
	v_exp_f32_e32 v66, v66
	v_exp_f32_e32 v67, v67
	v_exp_f32_e32 v68, v68
	v_exp_f32_e32 v69, v69
	v_exp_f32_e32 v70, v70
	v_exp_f32_e32 v71, v71
	v_exp_f32_e32 v72, v72
	v_add_f32_e32 v73, 1.0, v73
	v_add_f32_e32 v66, 1.0, v66
	v_add_f32_e32 v67, 1.0, v67
	v_add_f32_e32 v68, 1.0, v68
	v_add_f32_e32 v69, 1.0, v69
	v_add_f32_e32 v70, 1.0, v70
	v_add_f32_e32 v71, 1.0, v71
	v_add_f32_e32 v72, 1.0, v72
	v_rcp_f32_e32 v73, v73
	v_rcp_f32_e32 v66, v66
	v_rcp_f32_e32 v67, v67
	v_rcp_f32_e32 v68, v68
	v_rcp_f32_e32 v69, v69
	v_rcp_f32_e32 v70, v70
	v_rcp_f32_e32 v71, v71
	v_rcp_f32_e32 v72, v72
	v_mul_f32_e32 v51, v51, v73
	v_mul_f32_e32 v65, v65, v66
	v_mul_f32_e32 v57, v57, v67
	v_mul_f32_e32 v61, v61, v68
	v_mul_f32_e32 v59, v59, v69
	v_mul_f32_e32 v63, v63, v70
	v_mul_f32_e32 v49, v49, v71
	v_mul_f32_e32 v53, v53, v72
	v_mul_f32_e32 v51, v50, v51
	v_mul_f32_e32 v64, v64, v65
	v_mul_f32_e32 v56, v56, v57
	v_mul_f32_e32 v57, v60, v61
	v_mul_f32_e32 v58, v58, v59
	v_mul_f32_e32 v59, v62, v63
	v_mul_f32_e32 v60, v48, v49
	v_mul_f32_e32 v52, v52, v53
	v_cvt_pk_bf16_f32 v48, v64, v56
	v_cvt_pk_bf16_f32 v49, v57, v58
	v_cvt_pk_bf16_f32 v50, v59, v60
	v_cvt_pk_bf16_f32 v51, v52, v51
	global_store_dwordx4 v[54:55], v[48:51], off
	s_nop 0
	s_nop 0
	v_mov_b32_e32 v49, v40
	v_mov_b32_e32 v40, v45
	v_mov_b32_e32 v45, v42
	v_mov_b32_e32 v42, v47
	v_mov_b32_e32 v47, v32
	v_mov_b32_e32 v32, v37
	v_mov_b32_e32 v37, v34
	v_mov_b32_e32 v34, v39
	v_mov_b32_e32 v48, v44
	v_mov_b32_e32 v44, v46
	v_mov_b32_e32 v46, v36
	v_mov_b32_e32 v36, v38
	v_add_u32_e32 v38, 0x90, v144
	s_nop 0
	v_fmamk_f32 v39, v175, 0x3a800000, v154
	v_mul_f32_e32 v50, 0x4b800000, v39
	v_cmp_gt_f32_e32 vcc, s40, v39
	s_nop 1
	v_cndmask_b32_e32 v39, v39, v50, vcc
	v_rsq_f32_e32 v50, v39
	v_mad_i64_i32 v[38:39], s[0:1], v38, s41, v[120:121]
	v_lshl_add_u64 v[38:39], v[38:39], 0, v[122:123]
	v_mul_f32_e32 v51, 0x45800000, v50
	v_cndmask_b32_e32 v50, v50, v51, vcc
	v_pk_mul_f32 v[34:35], v[34:35], v[50:51] op_sel_hi:[1,0]
	v_pk_mul_f32 v[48:49], v[48:49], v[50:51] op_sel_hi:[1,0]
	v_pk_mul_f32 v[40:41], v[40:41], v[50:51] op_sel_hi:[1,0]
	v_pk_mul_f32 v[44:45], v[44:45], v[50:51] op_sel_hi:[1,0]
	v_pk_mul_f32 v[42:43], v[42:43], v[50:51] op_sel_hi:[1,0]
	v_pk_mul_f32 v[46:47], v[46:47], v[50:51] op_sel_hi:[1,0]
	v_pk_mul_f32 v[32:33], v[32:33], v[50:51] op_sel_hi:[1,0]
	v_pk_mul_f32 v[36:37], v[36:37], v[50:51] op_sel_hi:[1,0]
	v_mul_f32_e32 v57, 0xbfb8aa3b, v35
	v_mul_f32_e32 v50, 0xbfb8aa3b, v49
	v_mul_f32_e32 v51, 0xbfb8aa3b, v41
	v_mul_f32_e32 v52, 0xbfb8aa3b, v45
	v_mul_f32_e32 v53, 0xbfb8aa3b, v43
	v_mul_f32_e32 v54, 0xbfb8aa3b, v47
	v_mul_f32_e32 v55, 0xbfb8aa3b, v33
	v_mul_f32_e32 v56, 0xbfb8aa3b, v37
	v_exp_f32_e32 v57, v57
	v_exp_f32_e32 v50, v50
	v_exp_f32_e32 v51, v51
	v_exp_f32_e32 v52, v52
	v_exp_f32_e32 v53, v53
	v_exp_f32_e32 v54, v54
	v_exp_f32_e32 v55, v55
	v_exp_f32_e32 v56, v56
	v_add_f32_e32 v57, 1.0, v57
	v_add_f32_e32 v50, 1.0, v50
	v_add_f32_e32 v51, 1.0, v51
	v_add_f32_e32 v52, 1.0, v52
	v_add_f32_e32 v53, 1.0, v53
	v_add_f32_e32 v54, 1.0, v54
	v_add_f32_e32 v55, 1.0, v55
	v_add_f32_e32 v56, 1.0, v56
	v_rcp_f32_e32 v57, v57
	v_rcp_f32_e32 v50, v50
	v_rcp_f32_e32 v51, v51
	v_rcp_f32_e32 v52, v52
	v_rcp_f32_e32 v53, v53
	v_rcp_f32_e32 v54, v54
	v_rcp_f32_e32 v55, v55
	v_rcp_f32_e32 v56, v56
	v_mul_f32_e32 v35, v35, v57
	v_mul_f32_e32 v49, v49, v50
	v_mul_f32_e32 v41, v41, v51
	v_mul_f32_e32 v45, v45, v52
	v_mul_f32_e32 v43, v43, v53
	v_mul_f32_e32 v47, v47, v54
	v_mul_f32_e32 v33, v33, v55
	v_mul_f32_e32 v37, v37, v56
	v_mul_f32_e32 v35, v34, v35
	v_mul_f32_e32 v48, v48, v49
	v_mul_f32_e32 v40, v40, v41
	v_mul_f32_e32 v41, v44, v45
	v_mul_f32_e32 v42, v42, v43
	v_mul_f32_e32 v43, v46, v47
	v_mul_f32_e32 v44, v32, v33
	v_mul_f32_e32 v36, v36, v37
	v_cvt_pk_bf16_f32 v32, v48, v40
	v_cvt_pk_bf16_f32 v33, v41, v42
	v_cvt_pk_bf16_f32 v34, v43, v44
	v_cvt_pk_bf16_f32 v35, v36, v35
	global_store_dwordx4 v[38:39], v[32:35], off
	s_nop 0
	s_nop 0
	v_mov_b32_e32 v33, v24
	v_mov_b32_e32 v24, v29
	v_mov_b32_e32 v29, v26
	v_mov_b32_e32 v26, v31
	v_mov_b32_e32 v31, v16
	v_mov_b32_e32 v16, v21
	v_mov_b32_e32 v21, v18
	v_mov_b32_e32 v18, v23
	v_mov_b32_e32 v32, v28
	v_mov_b32_e32 v28, v30
	v_mov_b32_e32 v30, v20
	v_mov_b32_e32 v20, v22
	v_add_u32_e32 v22, 0xa0, v144
	s_nop 0
	v_fmamk_f32 v23, v176, 0x3a800000, v154
	v_mul_f32_e32 v34, 0x4b800000, v23
	v_cmp_gt_f32_e32 vcc, s40, v23
	s_nop 1
	v_cndmask_b32_e32 v23, v23, v34, vcc
	v_rsq_f32_e32 v34, v23
	v_mad_i64_i32 v[22:23], s[0:1], v22, s41, v[120:121]
	v_lshl_add_u64 v[22:23], v[22:23], 0, v[122:123]
	v_mul_f32_e32 v35, 0x45800000, v34
	v_cndmask_b32_e32 v34, v34, v35, vcc
	v_pk_mul_f32 v[18:19], v[18:19], v[34:35] op_sel_hi:[1,0]
	v_pk_mul_f32 v[32:33], v[32:33], v[34:35] op_sel_hi:[1,0]
	v_pk_mul_f32 v[24:25], v[24:25], v[34:35] op_sel_hi:[1,0]
	v_pk_mul_f32 v[28:29], v[28:29], v[34:35] op_sel_hi:[1,0]
	v_pk_mul_f32 v[26:27], v[26:27], v[34:35] op_sel_hi:[1,0]
	v_pk_mul_f32 v[30:31], v[30:31], v[34:35] op_sel_hi:[1,0]
	v_pk_mul_f32 v[16:17], v[16:17], v[34:35] op_sel_hi:[1,0]
	v_pk_mul_f32 v[20:21], v[20:21], v[34:35] op_sel_hi:[1,0]
	v_mul_f32_e32 v41, 0xbfb8aa3b, v19
	v_mul_f32_e32 v34, 0xbfb8aa3b, v33
	v_mul_f32_e32 v35, 0xbfb8aa3b, v25
	v_mul_f32_e32 v36, 0xbfb8aa3b, v29
	v_mul_f32_e32 v37, 0xbfb8aa3b, v27
	v_mul_f32_e32 v38, 0xbfb8aa3b, v31
	v_mul_f32_e32 v39, 0xbfb8aa3b, v17
	v_mul_f32_e32 v40, 0xbfb8aa3b, v21
	v_exp_f32_e32 v41, v41
	v_exp_f32_e32 v34, v34
	v_exp_f32_e32 v35, v35
	v_exp_f32_e32 v36, v36
	v_exp_f32_e32 v37, v37
	v_exp_f32_e32 v38, v38
	v_exp_f32_e32 v39, v39
	v_exp_f32_e32 v40, v40
	v_add_f32_e32 v41, 1.0, v41
	v_add_f32_e32 v34, 1.0, v34
	v_add_f32_e32 v35, 1.0, v35
	v_add_f32_e32 v36, 1.0, v36
	v_add_f32_e32 v37, 1.0, v37
	v_add_f32_e32 v38, 1.0, v38
	v_add_f32_e32 v39, 1.0, v39
	v_add_f32_e32 v40, 1.0, v40
	v_rcp_f32_e32 v41, v41
	v_rcp_f32_e32 v34, v34
	v_rcp_f32_e32 v35, v35
	v_rcp_f32_e32 v36, v36
	v_rcp_f32_e32 v37, v37
	v_rcp_f32_e32 v38, v38
	v_rcp_f32_e32 v39, v39
	v_rcp_f32_e32 v40, v40
	v_mul_f32_e32 v19, v19, v41
	v_mul_f32_e32 v33, v33, v34
	v_mul_f32_e32 v25, v25, v35
	v_mul_f32_e32 v29, v29, v36
	v_mul_f32_e32 v27, v27, v37
	v_mul_f32_e32 v31, v31, v38
	v_mul_f32_e32 v17, v17, v39
	v_mul_f32_e32 v21, v21, v40
	v_mul_f32_e32 v19, v18, v19
	v_mul_f32_e32 v32, v32, v33
	v_mul_f32_e32 v24, v24, v25
	v_mul_f32_e32 v25, v28, v29
	v_mul_f32_e32 v26, v26, v27
	v_mul_f32_e32 v27, v30, v31
	v_mul_f32_e32 v28, v16, v17
	v_mul_f32_e32 v20, v20, v21
	v_cvt_pk_bf16_f32 v16, v32, v24
	v_cvt_pk_bf16_f32 v17, v25, v26
	v_cvt_pk_bf16_f32 v18, v27, v28
	v_cvt_pk_bf16_f32 v19, v20, v19
	global_store_dwordx4 v[22:23], v[16:19], off
	s_nop 0
	s_andn2_b64 vcc, exec, s[4:5]
	v_mov_b32_e32 v17, v8
	v_mov_b32_e32 v8, v13
	v_mov_b32_e32 v13, v10
	v_mov_b32_e32 v10, v15
	v_mov_b32_e32 v15, v0
	v_mov_b32_e32 v0, v5
	v_mov_b32_e32 v5, v2
	v_mov_b32_e32 v2, v7
	v_mov_b32_e32 v16, v12
	v_mov_b32_e32 v12, v14
	v_mov_b32_e32 v14, v4
	v_mov_b32_e32 v4, v6
	v_add_u32_e32 v6, 0xb0, v144
	s_nop 0
	v_fmamk_f32 v7, v177, 0x3a800000, v154
	v_mul_f32_e32 v18, 0x4b800000, v7
	v_cmp_gt_f32_e64 s[0:1], s40, v7
	s_nop 1
	v_cndmask_b32_e64 v7, v7, v18, s[0:1]
	v_rsq_f32_e32 v18, v7
	v_mad_i64_i32 v[6:7], s[10:11], v6, s41, v[120:121]
	v_lshl_add_u64 v[6:7], v[6:7], 0, v[122:123]
	v_mul_f32_e32 v19, 0x45800000, v18
	v_cndmask_b32_e64 v18, v18, v19, s[0:1]
	v_pk_mul_f32 v[2:3], v[2:3], v[18:19] op_sel_hi:[1,0]
	v_pk_mul_f32 v[16:17], v[16:17], v[18:19] op_sel_hi:[1,0]
	v_pk_mul_f32 v[8:9], v[8:9], v[18:19] op_sel_hi:[1,0]
	v_pk_mul_f32 v[12:13], v[12:13], v[18:19] op_sel_hi:[1,0]
	v_pk_mul_f32 v[10:11], v[10:11], v[18:19] op_sel_hi:[1,0]
	v_pk_mul_f32 v[14:15], v[14:15], v[18:19] op_sel_hi:[1,0]
	v_pk_mul_f32 v[0:1], v[0:1], v[18:19] op_sel_hi:[1,0]
	v_pk_mul_f32 v[4:5], v[4:5], v[18:19] op_sel_hi:[1,0]
	v_mul_f32_e32 v25, 0xbfb8aa3b, v3
	v_mul_f32_e32 v18, 0xbfb8aa3b, v17
	v_mul_f32_e32 v19, 0xbfb8aa3b, v9
	v_mul_f32_e32 v20, 0xbfb8aa3b, v13
	v_mul_f32_e32 v21, 0xbfb8aa3b, v11
	v_mul_f32_e32 v22, 0xbfb8aa3b, v15
	v_mul_f32_e32 v23, 0xbfb8aa3b, v1
	v_mul_f32_e32 v24, 0xbfb8aa3b, v5
	v_exp_f32_e32 v25, v25
	v_exp_f32_e32 v18, v18
	v_exp_f32_e32 v19, v19
	v_exp_f32_e32 v20, v20
	v_exp_f32_e32 v21, v21
	v_exp_f32_e32 v22, v22
	v_exp_f32_e32 v23, v23
	v_exp_f32_e32 v24, v24
	v_add_f32_e32 v25, 1.0, v25
	v_add_f32_e32 v18, 1.0, v18
	v_add_f32_e32 v19, 1.0, v19
	v_add_f32_e32 v20, 1.0, v20
	v_add_f32_e32 v21, 1.0, v21
	v_add_f32_e32 v22, 1.0, v22
	v_add_f32_e32 v23, 1.0, v23
	v_add_f32_e32 v24, 1.0, v24
	v_rcp_f32_e32 v25, v25
	v_rcp_f32_e32 v18, v18
	v_rcp_f32_e32 v19, v19
	v_rcp_f32_e32 v20, v20
	v_rcp_f32_e32 v21, v21
	v_rcp_f32_e32 v22, v22
	v_rcp_f32_e32 v23, v23
	v_rcp_f32_e32 v24, v24
	v_mul_f32_e32 v3, v3, v25
	v_mul_f32_e32 v17, v17, v18
	v_mul_f32_e32 v9, v9, v19
	v_mul_f32_e32 v13, v13, v20
	v_mul_f32_e32 v11, v11, v21
	v_mul_f32_e32 v15, v15, v22
	v_mul_f32_e32 v1, v1, v23
	v_mul_f32_e32 v5, v5, v24
	v_mul_f32_e32 v3, v2, v3
	s_mov_b64 s[0:1], -1
	v_mul_f32_e32 v16, v16, v17
	v_mul_f32_e32 v8, v8, v9
	v_mul_f32_e32 v9, v12, v13
	v_mul_f32_e32 v10, v10, v11
	v_mul_f32_e32 v11, v14, v15
	v_mul_f32_e32 v12, v0, v1
	v_mul_f32_e32 v4, v4, v5
	v_cvt_pk_bf16_f32 v0, v16, v8
	v_cvt_pk_bf16_f32 v1, v9, v10
	v_cvt_pk_bf16_f32 v2, v11, v12
	v_cvt_pk_bf16_f32 v3, v4, v3
	global_store_dwordx4 v[6:7], v[0:3], off
	s_cbranch_vccnz .LBB0_999
	s_andn2_b64 vcc, exec, s[6:7]
	s_cbranch_vccnz .LBB0_998
	s_barrier
	s_branch .LBB0_998
